# P6 hand-written prompt path: the next prompt item's first 16 rows are loaded during the current item's last batch (cross-item prefetch), batch-0 wait reduced to one counted vmcnt(32)
# baseline (speedup 1.0000x reference)
; __device__ __forceinline__ void act_item(int item, u16* UP, const u16* HALO, const float* sconv, const float* wconv, const float* bconv, float* out, int lane) {
;     ...
;     for (int tb = 0; tb < 64; tb += 16) {
;         unsigned gw[16], vw[16];
; #pragma unroll
;         for (int t = 0; t < 16; ++t) { const size_t row = (size_t)rb * 64 + tb + t; gw[t] = *(const unsigned*)(UP + row * FF2 + j0); vw[t] = *(const unsigned*)(UP + row * FF2 + FF + j0); }
.Lact_rows:
	s_cmp_eq_u32 s97, 1
	s_cbranch_scc1 .Lact_pf_have
	global_load_dword v160, v2, s[64:65]
	global_load_dword v161, v3, s[64:65]
	s_add_u32 s64, s64, 0x2c00
	s_addc_u32 s65, s65, 0
	global_load_dword v162, v2, s[64:65]
	global_load_dword v163, v3, s[64:65]
	s_add_u32 s64, s64, 0x2c00
	s_addc_u32 s65, s65, 0
	global_load_dword v164, v2, s[64:65]
	global_load_dword v165, v3, s[64:65]
	s_add_u32 s64, s64, 0x2c00
	s_addc_u32 s65, s65, 0
	global_load_dword v166, v2, s[64:65]
	global_load_dword v167, v3, s[64:65]
	s_add_u32 s64, s64, 0x2c00
	s_addc_u32 s65, s65, 0
	global_load_dword v168, v2, s[64:65]
	global_load_dword v169, v3, s[64:65]
	s_add_u32 s64, s64, 0x2c00
	s_addc_u32 s65, s65, 0
	global_load_dword v170, v2, s[64:65]
	global_load_dword v171, v3, s[64:65]
	s_add_u32 s64, s64, 0x2c00
	s_addc_u32 s65, s65, 0
	global_load_dword v172, v2, s[64:65]
	global_load_dword v173, v3, s[64:65]
	s_add_u32 s64, s64, 0x2c00
	s_addc_u32 s65, s65, 0
	global_load_dword v174, v2, s[64:65]
	global_load_dword v175, v3, s[64:65]
	s_add_u32 s64, s64, 0x2c00
	s_addc_u32 s65, s65, 0
	global_load_dword v176, v2, s[64:65]
	global_load_dword v177, v3, s[64:65]
	s_add_u32 s64, s64, 0x2c00
	s_addc_u32 s65, s65, 0
	global_load_dword v178, v2, s[64:65]
	global_load_dword v179, v3, s[64:65]
	s_add_u32 s64, s64, 0x2c00
	s_addc_u32 s65, s65, 0
	global_load_dword v180, v2, s[64:65]
	global_load_dword v181, v3, s[64:65]
	s_add_u32 s64, s64, 0x2c00
	s_addc_u32 s65, s65, 0
	global_load_dword v182, v2, s[64:65]
	global_load_dword v183, v3, s[64:65]
	s_add_u32 s64, s64, 0x2c00
	s_addc_u32 s65, s65, 0
	global_load_dword v184, v2, s[64:65]
	global_load_dword v185, v3, s[64:65]
	s_add_u32 s64, s64, 0x2c00
	s_addc_u32 s65, s65, 0
	global_load_dword v186, v2, s[64:65]
	global_load_dword v187, v3, s[64:65]
	s_add_u32 s64, s64, 0x2c00
	s_addc_u32 s65, s65, 0
	global_load_dword v188, v2, s[64:65]
	global_load_dword v189, v3, s[64:65]
	s_add_u32 s64, s64, 0x2c00
	s_addc_u32 s65, s65, 0
	global_load_dword v190, v2, s[64:65]
	global_load_dword v191, v3, s[64:65]
	s_add_u32 s64, s64, 0x2c00
	s_addc_u32 s65, s65, 0
	s_branch .Lact_pf_go
.Lact_pf_have:
	s_add_u32 s64, s64, 0x2c000
	s_addc_u32 s65, s65, 0
.Lact_pf_go:
	s_mov_b32 s97, 0
	global_load_dword v192, v2, s[64:65]
	global_load_dword v193, v3, s[64:65]
	s_add_u32 s64, s64, 0x2c00
	s_addc_u32 s65, s65, 0
	global_load_dword v194, v2, s[64:65]
	global_load_dword v195, v3, s[64:65]
	s_add_u32 s64, s64, 0x2c00
	s_addc_u32 s65, s65, 0
	global_load_dword v196, v2, s[64:65]
	global_load_dword v197, v3, s[64:65]
	s_add_u32 s64, s64, 0x2c00
	s_addc_u32 s65, s65, 0
	global_load_dword v198, v2, s[64:65]
	global_load_dword v199, v3, s[64:65]
	s_add_u32 s64, s64, 0x2c00
	s_addc_u32 s65, s65, 0
	global_load_dword v200, v2, s[64:65]
	global_load_dword v201, v3, s[64:65]
	s_add_u32 s64, s64, 0x2c00
	s_addc_u32 s65, s65, 0
	global_load_dword v202, v2, s[64:65]
	global_load_dword v203, v3, s[64:65]
	s_add_u32 s64, s64, 0x2c00
	s_addc_u32 s65, s65, 0
	global_load_dword v204, v2, s[64:65]
	global_load_dword v205, v3, s[64:65]
	s_add_u32 s64, s64, 0x2c00
	s_addc_u32 s65, s65, 0
	global_load_dword v206, v2, s[64:65]
	global_load_dword v207, v3, s[64:65]
	s_add_u32 s64, s64, 0x2c00
	s_addc_u32 s65, s65, 0
	global_load_dword v208, v2, s[64:65]
	global_load_dword v209, v3, s[64:65]
	s_add_u32 s64, s64, 0x2c00
	s_addc_u32 s65, s65, 0
	global_load_dword v210, v2, s[64:65]
	global_load_dword v211, v3, s[64:65]
	s_add_u32 s64, s64, 0x2c00
	s_addc_u32 s65, s65, 0
	global_load_dword v212, v2, s[64:65]
	global_load_dword v213, v3, s[64:65]
	s_add_u32 s64, s64, 0x2c00
	s_addc_u32 s65, s65, 0
	global_load_dword v214, v2, s[64:65]
	global_load_dword v215, v3, s[64:65]
	s_add_u32 s64, s64, 0x2c00
	s_addc_u32 s65, s65, 0
	global_load_dword v216, v2, s[64:65]
	global_load_dword v217, v3, s[64:65]
	s_add_u32 s64, s64, 0x2c00
	s_addc_u32 s65, s65, 0
	global_load_dword v218, v2, s[64:65]
	global_load_dword v219, v3, s[64:65]
	s_add_u32 s64, s64, 0x2c00
	s_addc_u32 s65, s65, 0
	global_load_dword v220, v2, s[64:65]
	global_load_dword v221, v3, s[64:65]
	s_add_u32 s64, s64, 0x2c00
	s_addc_u32 s65, s65, 0
	global_load_dword v222, v2, s[64:65]
	global_load_dword v223, v3, s[64:65]
	s_add_u32 s64, s64, 0x2c00
	s_addc_u32 s65, s65, 0
	s_waitcnt vmcnt(32)
; __device__ __forceinline__ float bf2f(unsigned b) { return __uint_as_float(b << 16); }
; __device__ __forceinline__ unsigned pk2(float lo, float hi) { unsigned r; asm("v_cvt_pk_bf16_f32 %0, %1, %2" : "=v"(r) : "v"(lo), "v"(hi)); return r; }
; __device__ __forceinline__ float gelu_t(float x) { return x * __builtin_amdgcn_rcpf(1.f + __expf(-1.5957691216057308f * (x + 0.044715f * x * x * x))); }
; __device__ __forceinline__ void act_item(int item, u16* UP, const u16* HALO, const float* sconv, const float* wconv, const float* bconv, float* out, int lane) {
;     ...
;         for (int t = 0; t < 16; ++t) {
;             const int row = rb * 64 + tb + t;
;             if (sample && (t & 3) == 0) { const int ns = (row - TP) >> 2; const float* s0 = sconv + (size_t)ns * 2 * FF2;
;                 const f32x2 a = *(const f32x2*)(s0 + j0), b = *(const f32x2*)(s0 + FF + j0), c = *(const f32x2*)(s0 + FF2 + j0), dd = *(const f32x2*)(s0 + FF2 + FF + j0);
;                 g2[0] = a.x; g2[1] = a.y; v2[0] = b.x; v2[1] = b.y; g1[0] = c.x; g1[1] = c.y; v1[0] = dd.x; v1[1] = dd.y; }
;             const float g0[2] = {bf2f(gw[t] & 0xffffu), bf2f(gw[t] >> 16)}, v0[2] = {bf2f(vw[t] & 0xffffu), bf2f(vw[t] >> 16)};
;             float res[2];
; #pragma unroll
;             for (int p = 0; p < 2; ++p) { const float cgv = bg[p] + wgt[0][p] * g2[p] + wgt[1][p] * g1[p] + wgt[2][p] * g0[p];
;                 const float cvv = bv[p] + wvl[0][p] * v2[p] + wvl[1][p] * v1[p] + wvl[2][p] * v0[p]; res[p] = gelu_t(cgv) * cvv;
;                 g2[p] = g1[p]; g1[p] = g0[p]; v2[p] = v1[p]; v1[p] = v0[p]; }
;             *(unsigned*)(UP + (size_t)row * FF2 + j0) = pk2(res[0], res[1]);
	v_lshlrev_b32_e32 v24, 16, v226
	v_and_b32_e32 v25, 0xffff0000, v226
	v_lshlrev_b32_e32 v26, 16, v227
	v_and_b32_e32 v27, 0xffff0000, v227
	v_lshlrev_b32_e32 v28, 16, v228
	v_and_b32_e32 v29, 0xffff0000, v228
	v_lshlrev_b32_e32 v30, 16, v229
	v_and_b32_e32 v31, 0xffff0000, v229
	v_lshlrev_b32_e32 v20, 16, v160
	v_and_b32_e32 v21, 0xffff0000, v160
	v_lshlrev_b32_e32 v22, 16, v161
	v_and_b32_e32 v23, 0xffff0000, v161
	v_pk_fma_f32 v[32:33], v[4:5], v[24:25], v[16:17]
	v_pk_fma_f32 v[34:35], v[6:7], v[26:27], v[18:19]
	v_pk_fma_f32 v[32:33], v[8:9], v[28:29], v[32:33]
	v_pk_fma_f32 v[34:35], v[10:11], v[30:31], v[34:35]
	v_pk_fma_f32 v[32:33], v[12:13], v[20:21], v[32:33]
	v_pk_fma_f32 v[34:35], v[14:15], v[22:23], v[34:35]
	v_pk_mul_f32 v[36:37], v[32:33], s[58:59]
	v_pk_mul_f32 v[36:37], v[32:33], v[36:37]
	v_pk_fma_f32 v[36:37], v[32:33], v[36:37], v[32:33]
	v_pk_mul_f32 v[36:37], v[36:37], s[60:61]
	v_pk_mul_f32 v[36:37], v[36:37], s[68:69]
	v_exp_f32_e32 v38, v36
	v_exp_f32_e32 v39, v37
	s_nop 0
	v_pk_add_f32 v[38:39], v[38:39], s[82:83]
	v_rcp_f32_e32 v38, v38
	v_rcp_f32_e32 v39, v39
	s_nop 0
	v_pk_mul_f32 v[36:37], v[32:33], v[38:39]
	v_pk_mul_f32 v[36:37], v[34:35], v[36:37]
	v_cvt_pk_bf16_f32 v224, v36, v37
	global_store_dword v2, v224, s[66:67]
	s_add_u32 s66, s66, 0x2c00
	s_addc_u32 s67, s67, 0
	v_lshlrev_b32_e32 v24, 16, v162
	v_and_b32_e32 v25, 0xffff0000, v162
	v_lshlrev_b32_e32 v26, 16, v163
	v_and_b32_e32 v27, 0xffff0000, v163
	v_pk_fma_f32 v[32:33], v[4:5], v[28:29], v[16:17]
	v_pk_fma_f32 v[34:35], v[6:7], v[30:31], v[18:19]
	v_pk_fma_f32 v[32:33], v[8:9], v[20:21], v[32:33]
	v_pk_fma_f32 v[34:35], v[10:11], v[22:23], v[34:35]
	v_pk_fma_f32 v[32:33], v[12:13], v[24:25], v[32:33]
	v_pk_fma_f32 v[34:35], v[14:15], v[26:27], v[34:35]
	v_pk_mul_f32 v[36:37], v[32:33], s[58:59]
	v_pk_mul_f32 v[36:37], v[32:33], v[36:37]
	v_pk_fma_f32 v[36:37], v[32:33], v[36:37], v[32:33]
	v_pk_mul_f32 v[36:37], v[36:37], s[60:61]
	v_pk_mul_f32 v[36:37], v[36:37], s[68:69]
	v_exp_f32_e32 v38, v36
	v_exp_f32_e32 v39, v37
	s_nop 0
	v_pk_add_f32 v[38:39], v[38:39], s[82:83]
	v_rcp_f32_e32 v38, v38
	v_rcp_f32_e32 v39, v39
	s_nop 0
	v_pk_mul_f32 v[36:37], v[32:33], v[38:39]
	v_pk_mul_f32 v[36:37], v[34:35], v[36:37]
	v_cvt_pk_bf16_f32 v224, v36, v37
	global_store_dword v2, v224, s[66:67]
	s_add_u32 s66, s66, 0x2c00
	s_addc_u32 s67, s67, 0
	v_lshlrev_b32_e32 v28, 16, v164
	v_and_b32_e32 v29, 0xffff0000, v164
	v_lshlrev_b32_e32 v30, 16, v165
	v_and_b32_e32 v31, 0xffff0000, v165
	v_pk_fma_f32 v[32:33], v[4:5], v[20:21], v[16:17]
	v_pk_fma_f32 v[34:35], v[6:7], v[22:23], v[18:19]
	v_pk_fma_f32 v[32:33], v[8:9], v[24:25], v[32:33]
	v_pk_fma_f32 v[34:35], v[10:11], v[26:27], v[34:35]
	v_pk_fma_f32 v[32:33], v[12:13], v[28:29], v[32:33]
	v_pk_fma_f32 v[34:35], v[14:15], v[30:31], v[34:35]
	v_pk_mul_f32 v[36:37], v[32:33], s[58:59]
	v_pk_mul_f32 v[36:37], v[32:33], v[36:37]
	v_pk_fma_f32 v[36:37], v[32:33], v[36:37], v[32:33]
	v_pk_mul_f32 v[36:37], v[36:37], s[60:61]
	v_pk_mul_f32 v[36:37], v[36:37], s[68:69]
	v_exp_f32_e32 v38, v36
	v_exp_f32_e32 v39, v37
	s_nop 0
	v_pk_add_f32 v[38:39], v[38:39], s[82:83]
	v_rcp_f32_e32 v38, v38
	v_rcp_f32_e32 v39, v39
	s_nop 0
	v_pk_mul_f32 v[36:37], v[32:33], v[38:39]
	v_pk_mul_f32 v[36:37], v[34:35], v[36:37]
	v_cvt_pk_bf16_f32 v224, v36, v37
	global_store_dword v2, v224, s[66:67]
	s_add_u32 s66, s66, 0x2c00
	s_addc_u32 s67, s67, 0
	v_lshlrev_b32_e32 v20, 16, v166
	v_and_b32_e32 v21, 0xffff0000, v166
	v_lshlrev_b32_e32 v22, 16, v167
	v_and_b32_e32 v23, 0xffff0000, v167
	v_pk_fma_f32 v[32:33], v[4:5], v[24:25], v[16:17]
	v_pk_fma_f32 v[34:35], v[6:7], v[26:27], v[18:19]
	v_pk_fma_f32 v[32:33], v[8:9], v[28:29], v[32:33]
	v_pk_fma_f32 v[34:35], v[10:11], v[30:31], v[34:35]
	v_pk_fma_f32 v[32:33], v[12:13], v[20:21], v[32:33]
	v_pk_fma_f32 v[34:35], v[14:15], v[22:23], v[34:35]
	v_pk_mul_f32 v[36:37], v[32:33], s[58:59]
	v_pk_mul_f32 v[36:37], v[32:33], v[36:37]
	v_pk_fma_f32 v[36:37], v[32:33], v[36:37], v[32:33]
	v_pk_mul_f32 v[36:37], v[36:37], s[60:61]
	v_pk_mul_f32 v[36:37], v[36:37], s[68:69]
	v_exp_f32_e32 v38, v36
	v_exp_f32_e32 v39, v37
	s_nop 0
	v_pk_add_f32 v[38:39], v[38:39], s[82:83]
	v_rcp_f32_e32 v38, v38
	v_rcp_f32_e32 v39, v39
	s_nop 0
	v_pk_mul_f32 v[36:37], v[32:33], v[38:39]
	v_pk_mul_f32 v[36:37], v[34:35], v[36:37]
	v_cvt_pk_bf16_f32 v224, v36, v37
	global_store_dword v2, v224, s[66:67]
	s_add_u32 s66, s66, 0x2c00
	s_addc_u32 s67, s67, 0
	v_lshlrev_b32_e32 v24, 16, v168
	v_and_b32_e32 v25, 0xffff0000, v168
	v_lshlrev_b32_e32 v26, 16, v169
	v_and_b32_e32 v27, 0xffff0000, v169
	v_pk_fma_f32 v[32:33], v[4:5], v[28:29], v[16:17]
	v_pk_fma_f32 v[34:35], v[6:7], v[30:31], v[18:19]
	v_pk_fma_f32 v[32:33], v[8:9], v[20:21], v[32:33]
	v_pk_fma_f32 v[34:35], v[10:11], v[22:23], v[34:35]
	v_pk_fma_f32 v[32:33], v[12:13], v[24:25], v[32:33]
	v_pk_fma_f32 v[34:35], v[14:15], v[26:27], v[34:35]
	v_pk_mul_f32 v[36:37], v[32:33], s[58:59]
	v_pk_mul_f32 v[36:37], v[32:33], v[36:37]
	v_pk_fma_f32 v[36:37], v[32:33], v[36:37], v[32:33]
	v_pk_mul_f32 v[36:37], v[36:37], s[60:61]
	v_pk_mul_f32 v[36:37], v[36:37], s[68:69]
	v_exp_f32_e32 v38, v36
	v_exp_f32_e32 v39, v37
	s_nop 0
	v_pk_add_f32 v[38:39], v[38:39], s[82:83]
	v_rcp_f32_e32 v38, v38
	v_rcp_f32_e32 v39, v39
	s_nop 0
	v_pk_mul_f32 v[36:37], v[32:33], v[38:39]
	v_pk_mul_f32 v[36:37], v[34:35], v[36:37]
	v_cvt_pk_bf16_f32 v224, v36, v37
	global_store_dword v2, v224, s[66:67]
	s_add_u32 s66, s66, 0x2c00
	s_addc_u32 s67, s67, 0
	v_lshlrev_b32_e32 v28, 16, v170
	v_and_b32_e32 v29, 0xffff0000, v170
	v_lshlrev_b32_e32 v30, 16, v171
	v_and_b32_e32 v31, 0xffff0000, v171
; __device__ __forceinline__ float bf2f(unsigned b) { return __uint_as_float(b << 16); }
; __device__ __forceinline__ unsigned pk2(float lo, float hi) { unsigned r; asm("v_cvt_pk_bf16_f32 %0, %1, %2" : "=v"(r) : "v"(lo), "v"(hi)); return r; }
; __device__ __forceinline__ float gelu_t(float x) { return x * __builtin_amdgcn_rcpf(1.f + __expf(-1.5957691216057308f * (x + 0.044715f * x * x * x))); }
; __device__ __forceinline__ void act_item(int item, u16* UP, const u16* HALO, const float* sconv, const float* wconv, const float* bconv, float* out, int lane) {
;     ...
;         for (int t = 0; t < 16; ++t) {
;             const int row = rb * 64 + tb + t;
;             if (sample && (t & 3) == 0) { const int ns = (row - TP) >> 2; const float* s0 = sconv + (size_t)ns * 2 * FF2;
;                 const f32x2 a = *(const f32x2*)(s0 + j0), b = *(const f32x2*)(s0 + FF + j0), c = *(const f32x2*)(s0 + FF2 + j0), dd = *(const f32x2*)(s0 + FF2 + FF + j0);
;                 g2[0] = a.x; g2[1] = a.y; v2[0] = b.x; v2[1] = b.y; g1[0] = c.x; g1[1] = c.y; v1[0] = dd.x; v1[1] = dd.y; }
;             const float g0[2] = {bf2f(gw[t] & 0xffffu), bf2f(gw[t] >> 16)}, v0[2] = {bf2f(vw[t] & 0xffffu), bf2f(vw[t] >> 16)};
;             float res[2];
; #pragma unroll
;             for (int p = 0; p < 2; ++p) { const float cgv = bg[p] + wgt[0][p] * g2[p] + wgt[1][p] * g1[p] + wgt[2][p] * g0[p];
;                 const float cvv = bv[p] + wvl[0][p] * v2[p] + wvl[1][p] * v1[p] + wvl[2][p] * v0[p]; res[p] = gelu_t(cgv) * cvv;
;                 g2[p] = g1[p]; g1[p] = g0[p]; v2[p] = v1[p]; v1[p] = v0[p]; }
;             *(unsigned*)(UP + (size_t)row * FF2 + j0) = pk2(res[0], res[1]);
	v_pk_fma_f32 v[32:33], v[4:5], v[20:21], v[16:17]
	v_pk_fma_f32 v[34:35], v[6:7], v[22:23], v[18:19]
	v_pk_fma_f32 v[32:33], v[8:9], v[24:25], v[32:33]
	v_pk_fma_f32 v[34:35], v[10:11], v[26:27], v[34:35]
	v_pk_fma_f32 v[32:33], v[12:13], v[28:29], v[32:33]
	v_pk_fma_f32 v[34:35], v[14:15], v[30:31], v[34:35]
	v_pk_mul_f32 v[36:37], v[32:33], s[58:59]
	v_pk_mul_f32 v[36:37], v[32:33], v[36:37]
	v_pk_fma_f32 v[36:37], v[32:33], v[36:37], v[32:33]
	v_pk_mul_f32 v[36:37], v[36:37], s[60:61]
	v_pk_mul_f32 v[36:37], v[36:37], s[68:69]
	v_exp_f32_e32 v38, v36
	v_exp_f32_e32 v39, v37
	s_nop 0
	v_pk_add_f32 v[38:39], v[38:39], s[82:83]
	v_rcp_f32_e32 v38, v38
	v_rcp_f32_e32 v39, v39
	s_nop 0
	v_pk_mul_f32 v[36:37], v[32:33], v[38:39]
	v_pk_mul_f32 v[36:37], v[34:35], v[36:37]
	v_cvt_pk_bf16_f32 v224, v36, v37
	global_store_dword v2, v224, s[66:67]
	s_add_u32 s66, s66, 0x2c00
	s_addc_u32 s67, s67, 0
	v_lshlrev_b32_e32 v20, 16, v172
	v_and_b32_e32 v21, 0xffff0000, v172
	v_lshlrev_b32_e32 v22, 16, v173
	v_and_b32_e32 v23, 0xffff0000, v173
	v_pk_fma_f32 v[32:33], v[4:5], v[24:25], v[16:17]
	v_pk_fma_f32 v[34:35], v[6:7], v[26:27], v[18:19]
	v_pk_fma_f32 v[32:33], v[8:9], v[28:29], v[32:33]
	v_pk_fma_f32 v[34:35], v[10:11], v[30:31], v[34:35]
	v_pk_fma_f32 v[32:33], v[12:13], v[20:21], v[32:33]
	v_pk_fma_f32 v[34:35], v[14:15], v[22:23], v[34:35]
	v_pk_mul_f32 v[36:37], v[32:33], s[58:59]
	v_pk_mul_f32 v[36:37], v[32:33], v[36:37]
	v_pk_fma_f32 v[36:37], v[32:33], v[36:37], v[32:33]
	v_pk_mul_f32 v[36:37], v[36:37], s[60:61]
	v_pk_mul_f32 v[36:37], v[36:37], s[68:69]
	v_exp_f32_e32 v38, v36
	v_exp_f32_e32 v39, v37
	s_nop 0
	v_pk_add_f32 v[38:39], v[38:39], s[82:83]
	v_rcp_f32_e32 v38, v38
	v_rcp_f32_e32 v39, v39
	s_nop 0
	v_pk_mul_f32 v[36:37], v[32:33], v[38:39]
	v_pk_mul_f32 v[36:37], v[34:35], v[36:37]
	v_cvt_pk_bf16_f32 v224, v36, v37
	global_store_dword v2, v224, s[66:67]
	s_add_u32 s66, s66, 0x2c00
	s_addc_u32 s67, s67, 0
	v_lshlrev_b32_e32 v24, 16, v174
	v_and_b32_e32 v25, 0xffff0000, v174
	v_lshlrev_b32_e32 v26, 16, v175
	v_and_b32_e32 v27, 0xffff0000, v175
	v_pk_fma_f32 v[32:33], v[4:5], v[28:29], v[16:17]
	v_pk_fma_f32 v[34:35], v[6:7], v[30:31], v[18:19]
	v_pk_fma_f32 v[32:33], v[8:9], v[20:21], v[32:33]
	v_pk_fma_f32 v[34:35], v[10:11], v[22:23], v[34:35]
	v_pk_fma_f32 v[32:33], v[12:13], v[24:25], v[32:33]
	v_pk_fma_f32 v[34:35], v[14:15], v[26:27], v[34:35]
	v_pk_mul_f32 v[36:37], v[32:33], s[58:59]
	v_pk_mul_f32 v[36:37], v[32:33], v[36:37]
	v_pk_fma_f32 v[36:37], v[32:33], v[36:37], v[32:33]
	v_pk_mul_f32 v[36:37], v[36:37], s[60:61]
	v_pk_mul_f32 v[36:37], v[36:37], s[68:69]
	v_exp_f32_e32 v38, v36
	v_exp_f32_e32 v39, v37
	s_nop 0
	v_pk_add_f32 v[38:39], v[38:39], s[82:83]
	v_rcp_f32_e32 v38, v38
	v_rcp_f32_e32 v39, v39
	s_nop 0
	v_pk_mul_f32 v[36:37], v[32:33], v[38:39]
	v_pk_mul_f32 v[36:37], v[34:35], v[36:37]
	v_cvt_pk_bf16_f32 v224, v36, v37
	global_store_dword v2, v224, s[66:67]
	s_add_u32 s66, s66, 0x2c00
	s_addc_u32 s67, s67, 0
	v_lshlrev_b32_e32 v28, 16, v176
	v_and_b32_e32 v29, 0xffff0000, v176
	v_lshlrev_b32_e32 v30, 16, v177
	v_and_b32_e32 v31, 0xffff0000, v177
	v_pk_fma_f32 v[32:33], v[4:5], v[20:21], v[16:17]
	v_pk_fma_f32 v[34:35], v[6:7], v[22:23], v[18:19]
	v_pk_fma_f32 v[32:33], v[8:9], v[24:25], v[32:33]
	v_pk_fma_f32 v[34:35], v[10:11], v[26:27], v[34:35]
	v_pk_fma_f32 v[32:33], v[12:13], v[28:29], v[32:33]
	v_pk_fma_f32 v[34:35], v[14:15], v[30:31], v[34:35]
	v_pk_mul_f32 v[36:37], v[32:33], s[58:59]
	v_pk_mul_f32 v[36:37], v[32:33], v[36:37]
	v_pk_fma_f32 v[36:37], v[32:33], v[36:37], v[32:33]
	v_pk_mul_f32 v[36:37], v[36:37], s[60:61]
	v_pk_mul_f32 v[36:37], v[36:37], s[68:69]
	v_exp_f32_e32 v38, v36
	v_exp_f32_e32 v39, v37
	s_nop 0
	v_pk_add_f32 v[38:39], v[38:39], s[82:83]
	v_rcp_f32_e32 v38, v38
	v_rcp_f32_e32 v39, v39
	s_nop 0
	v_pk_mul_f32 v[36:37], v[32:33], v[38:39]
	v_pk_mul_f32 v[36:37], v[34:35], v[36:37]
	v_cvt_pk_bf16_f32 v224, v36, v37
	global_store_dword v2, v224, s[66:67]
	s_add_u32 s66, s66, 0x2c00
	s_addc_u32 s67, s67, 0
	v_lshlrev_b32_e32 v20, 16, v178
	v_and_b32_e32 v21, 0xffff0000, v178
	v_lshlrev_b32_e32 v22, 16, v179
	v_and_b32_e32 v23, 0xffff0000, v179
	v_pk_fma_f32 v[32:33], v[4:5], v[24:25], v[16:17]
	v_pk_fma_f32 v[34:35], v[6:7], v[26:27], v[18:19]
	v_pk_fma_f32 v[32:33], v[8:9], v[28:29], v[32:33]
	v_pk_fma_f32 v[34:35], v[10:11], v[30:31], v[34:35]
	v_pk_fma_f32 v[32:33], v[12:13], v[20:21], v[32:33]
	v_pk_fma_f32 v[34:35], v[14:15], v[22:23], v[34:35]
	v_pk_mul_f32 v[36:37], v[32:33], s[58:59]
	v_pk_mul_f32 v[36:37], v[32:33], v[36:37]
	v_pk_fma_f32 v[36:37], v[32:33], v[36:37], v[32:33]
	v_pk_mul_f32 v[36:37], v[36:37], s[60:61]
	v_pk_mul_f32 v[36:37], v[36:37], s[68:69]
	v_exp_f32_e32 v38, v36
	v_exp_f32_e32 v39, v37
	s_nop 0
	v_pk_add_f32 v[38:39], v[38:39], s[82:83]
	v_rcp_f32_e32 v38, v38
	v_rcp_f32_e32 v39, v39
	s_nop 0
	v_pk_mul_f32 v[36:37], v[32:33], v[38:39]
	v_pk_mul_f32 v[36:37], v[34:35], v[36:37]
	v_cvt_pk_bf16_f32 v224, v36, v37
	global_store_dword v2, v224, s[66:67]
	s_add_u32 s66, s66, 0x2c00
	s_addc_u32 s67, s67, 0
	v_lshlrev_b32_e32 v24, 16, v180
	v_and_b32_e32 v25, 0xffff0000, v180
	v_lshlrev_b32_e32 v26, 16, v181
	v_and_b32_e32 v27, 0xffff0000, v181
	v_pk_fma_f32 v[32:33], v[4:5], v[28:29], v[16:17]
	v_pk_fma_f32 v[34:35], v[6:7], v[30:31], v[18:19]
	v_pk_fma_f32 v[32:33], v[8:9], v[20:21], v[32:33]
	v_pk_fma_f32 v[34:35], v[10:11], v[22:23], v[34:35]
	v_pk_fma_f32 v[32:33], v[12:13], v[24:25], v[32:33]
	v_pk_fma_f32 v[34:35], v[14:15], v[26:27], v[34:35]
	v_pk_mul_f32 v[36:37], v[32:33], s[58:59]
	v_pk_mul_f32 v[36:37], v[32:33], v[36:37]
; __device__ __forceinline__ float bf2f(unsigned b) { return __uint_as_float(b << 16); }
; __device__ __forceinline__ unsigned pk2(float lo, float hi) { unsigned r; asm("v_cvt_pk_bf16_f32 %0, %1, %2" : "=v"(r) : "v"(lo), "v"(hi)); return r; }
; __device__ __forceinline__ float gelu_t(float x) { return x * __builtin_amdgcn_rcpf(1.f + __expf(-1.5957691216057308f * (x + 0.044715f * x * x * x))); }
; __device__ __forceinline__ void act_item(int item, u16* UP, const u16* HALO, const float* sconv, const float* wconv, const float* bconv, float* out, int lane) {
;     ...
;         for (int t = 0; t < 16; ++t) {
;             const int row = rb * 64 + tb + t;
;             if (sample && (t & 3) == 0) { const int ns = (row - TP) >> 2; const float* s0 = sconv + (size_t)ns * 2 * FF2;
;                 const f32x2 a = *(const f32x2*)(s0 + j0), b = *(const f32x2*)(s0 + FF + j0), c = *(const f32x2*)(s0 + FF2 + j0), dd = *(const f32x2*)(s0 + FF2 + FF + j0);
;                 g2[0] = a.x; g2[1] = a.y; v2[0] = b.x; v2[1] = b.y; g1[0] = c.x; g1[1] = c.y; v1[0] = dd.x; v1[1] = dd.y; }
;             const float g0[2] = {bf2f(gw[t] & 0xffffu), bf2f(gw[t] >> 16)}, v0[2] = {bf2f(vw[t] & 0xffffu), bf2f(vw[t] >> 16)};
;             float res[2];
; #pragma unroll
;             for (int p = 0; p < 2; ++p) { const float cgv = bg[p] + wgt[0][p] * g2[p] + wgt[1][p] * g1[p] + wgt[2][p] * g0[p];
;                 const float cvv = bv[p] + wvl[0][p] * v2[p] + wvl[1][p] * v1[p] + wvl[2][p] * v0[p]; res[p] = gelu_t(cgv) * cvv;
;                 g2[p] = g1[p]; g1[p] = g0[p]; v2[p] = v1[p]; v1[p] = v0[p]; }
;             *(unsigned*)(UP + (size_t)row * FF2 + j0) = pk2(res[0], res[1]);
	v_pk_fma_f32 v[36:37], v[32:33], v[36:37], v[32:33]
	v_pk_mul_f32 v[36:37], v[36:37], s[60:61]
	v_pk_mul_f32 v[36:37], v[36:37], s[68:69]
	v_exp_f32_e32 v38, v36
	v_exp_f32_e32 v39, v37
	s_nop 0
	v_pk_add_f32 v[38:39], v[38:39], s[82:83]
	v_rcp_f32_e32 v38, v38
	v_rcp_f32_e32 v39, v39
	s_nop 0
	v_pk_mul_f32 v[36:37], v[32:33], v[38:39]
	v_pk_mul_f32 v[36:37], v[34:35], v[36:37]
	v_cvt_pk_bf16_f32 v224, v36, v37
	global_store_dword v2, v224, s[66:67]
	s_add_u32 s66, s66, 0x2c00
	s_addc_u32 s67, s67, 0
	v_lshlrev_b32_e32 v28, 16, v182
	v_and_b32_e32 v29, 0xffff0000, v182
	v_lshlrev_b32_e32 v30, 16, v183
	v_and_b32_e32 v31, 0xffff0000, v183
	v_pk_fma_f32 v[32:33], v[4:5], v[20:21], v[16:17]
	v_pk_fma_f32 v[34:35], v[6:7], v[22:23], v[18:19]
	v_pk_fma_f32 v[32:33], v[8:9], v[24:25], v[32:33]
	v_pk_fma_f32 v[34:35], v[10:11], v[26:27], v[34:35]
	v_pk_fma_f32 v[32:33], v[12:13], v[28:29], v[32:33]
	v_pk_fma_f32 v[34:35], v[14:15], v[30:31], v[34:35]
	v_pk_mul_f32 v[36:37], v[32:33], s[58:59]
	v_pk_mul_f32 v[36:37], v[32:33], v[36:37]
	v_pk_fma_f32 v[36:37], v[32:33], v[36:37], v[32:33]
	v_pk_mul_f32 v[36:37], v[36:37], s[60:61]
	v_pk_mul_f32 v[36:37], v[36:37], s[68:69]
	v_exp_f32_e32 v38, v36
	v_exp_f32_e32 v39, v37
	s_nop 0
	v_pk_add_f32 v[38:39], v[38:39], s[82:83]
	v_rcp_f32_e32 v38, v38
	v_rcp_f32_e32 v39, v39
	s_nop 0
	v_pk_mul_f32 v[36:37], v[32:33], v[38:39]
	v_pk_mul_f32 v[36:37], v[34:35], v[36:37]
	v_cvt_pk_bf16_f32 v224, v36, v37
	global_store_dword v2, v224, s[66:67]
	s_add_u32 s66, s66, 0x2c00
	s_addc_u32 s67, s67, 0
	v_lshlrev_b32_e32 v20, 16, v184
	v_and_b32_e32 v21, 0xffff0000, v184
	v_lshlrev_b32_e32 v22, 16, v185
	v_and_b32_e32 v23, 0xffff0000, v185
	v_pk_fma_f32 v[32:33], v[4:5], v[24:25], v[16:17]
	v_pk_fma_f32 v[34:35], v[6:7], v[26:27], v[18:19]
	v_pk_fma_f32 v[32:33], v[8:9], v[28:29], v[32:33]
	v_pk_fma_f32 v[34:35], v[10:11], v[30:31], v[34:35]
	v_pk_fma_f32 v[32:33], v[12:13], v[20:21], v[32:33]
	v_pk_fma_f32 v[34:35], v[14:15], v[22:23], v[34:35]
	v_pk_mul_f32 v[36:37], v[32:33], s[58:59]
	v_pk_mul_f32 v[36:37], v[32:33], v[36:37]
	v_pk_fma_f32 v[36:37], v[32:33], v[36:37], v[32:33]
	v_pk_mul_f32 v[36:37], v[36:37], s[60:61]
	v_pk_mul_f32 v[36:37], v[36:37], s[68:69]
	v_exp_f32_e32 v38, v36
	v_exp_f32_e32 v39, v37
	s_nop 0
	v_pk_add_f32 v[38:39], v[38:39], s[82:83]
	v_rcp_f32_e32 v38, v38
	v_rcp_f32_e32 v39, v39
	s_nop 0
	v_pk_mul_f32 v[36:37], v[32:33], v[38:39]
	v_pk_mul_f32 v[36:37], v[34:35], v[36:37]
	v_cvt_pk_bf16_f32 v224, v36, v37
	global_store_dword v2, v224, s[66:67]
	s_add_u32 s66, s66, 0x2c00
	s_addc_u32 s67, s67, 0
	v_lshlrev_b32_e32 v24, 16, v186
	v_and_b32_e32 v25, 0xffff0000, v186
	v_lshlrev_b32_e32 v26, 16, v187
	v_and_b32_e32 v27, 0xffff0000, v187
	v_pk_fma_f32 v[32:33], v[4:5], v[28:29], v[16:17]
	v_pk_fma_f32 v[34:35], v[6:7], v[30:31], v[18:19]
	v_pk_fma_f32 v[32:33], v[8:9], v[20:21], v[32:33]
	v_pk_fma_f32 v[34:35], v[10:11], v[22:23], v[34:35]
	v_pk_fma_f32 v[32:33], v[12:13], v[24:25], v[32:33]
	v_pk_fma_f32 v[34:35], v[14:15], v[26:27], v[34:35]
	v_pk_mul_f32 v[36:37], v[32:33], s[58:59]
	v_pk_mul_f32 v[36:37], v[32:33], v[36:37]
	v_pk_fma_f32 v[36:37], v[32:33], v[36:37], v[32:33]
	v_pk_mul_f32 v[36:37], v[36:37], s[60:61]
	v_pk_mul_f32 v[36:37], v[36:37], s[68:69]
	v_exp_f32_e32 v38, v36
	v_exp_f32_e32 v39, v37
	s_nop 0
	v_pk_add_f32 v[38:39], v[38:39], s[82:83]
	v_rcp_f32_e32 v38, v38
	v_rcp_f32_e32 v39, v39
	s_nop 0
	v_pk_mul_f32 v[36:37], v[32:33], v[38:39]
	v_pk_mul_f32 v[36:37], v[34:35], v[36:37]
	v_cvt_pk_bf16_f32 v224, v36, v37
	global_store_dword v2, v224, s[66:67]
	s_add_u32 s66, s66, 0x2c00
	s_addc_u32 s67, s67, 0
	v_lshlrev_b32_e32 v28, 16, v188
	v_and_b32_e32 v29, 0xffff0000, v188
	v_lshlrev_b32_e32 v30, 16, v189
	v_and_b32_e32 v31, 0xffff0000, v189
	v_pk_fma_f32 v[32:33], v[4:5], v[20:21], v[16:17]
	v_pk_fma_f32 v[34:35], v[6:7], v[22:23], v[18:19]
	v_pk_fma_f32 v[32:33], v[8:9], v[24:25], v[32:33]
	v_pk_fma_f32 v[34:35], v[10:11], v[26:27], v[34:35]
	v_pk_fma_f32 v[32:33], v[12:13], v[28:29], v[32:33]
	v_pk_fma_f32 v[34:35], v[14:15], v[30:31], v[34:35]
	v_pk_mul_f32 v[36:37], v[32:33], s[58:59]
	v_pk_mul_f32 v[36:37], v[32:33], v[36:37]
	v_pk_fma_f32 v[36:37], v[32:33], v[36:37], v[32:33]
	v_pk_mul_f32 v[36:37], v[36:37], s[60:61]
	v_pk_mul_f32 v[36:37], v[36:37], s[68:69]
	v_exp_f32_e32 v38, v36
	v_exp_f32_e32 v39, v37
	s_nop 0
	v_pk_add_f32 v[38:39], v[38:39], s[82:83]
	v_rcp_f32_e32 v38, v38
	v_rcp_f32_e32 v39, v39
	s_nop 0
	v_pk_mul_f32 v[36:37], v[32:33], v[38:39]
	v_pk_mul_f32 v[36:37], v[34:35], v[36:37]
	v_cvt_pk_bf16_f32 v224, v36, v37
	global_store_dword v2, v224, s[66:67]
	s_add_u32 s66, s66, 0x2c00
	s_addc_u32 s67, s67, 0
	v_lshlrev_b32_e32 v20, 16, v190
	v_and_b32_e32 v21, 0xffff0000, v190
	v_lshlrev_b32_e32 v22, 16, v191
	v_and_b32_e32 v23, 0xffff0000, v191
	v_pk_fma_f32 v[32:33], v[4:5], v[24:25], v[16:17]
	v_pk_fma_f32 v[34:35], v[6:7], v[26:27], v[18:19]
	v_pk_fma_f32 v[32:33], v[8:9], v[28:29], v[32:33]
	v_pk_fma_f32 v[34:35], v[10:11], v[30:31], v[34:35]
	v_pk_fma_f32 v[32:33], v[12:13], v[20:21], v[32:33]
	v_pk_fma_f32 v[34:35], v[14:15], v[22:23], v[34:35]
	v_pk_mul_f32 v[36:37], v[32:33], s[58:59]
	v_pk_mul_f32 v[36:37], v[32:33], v[36:37]
	v_pk_fma_f32 v[36:37], v[32:33], v[36:37], v[32:33]
	v_pk_mul_f32 v[36:37], v[36:37], s[60:61]
	v_pk_mul_f32 v[36:37], v[36:37], s[68:69]
	v_exp_f32_e32 v38, v36
	v_exp_f32_e32 v39, v37
	s_nop 0
	v_pk_add_f32 v[38:39], v[38:39], s[82:83]
	v_rcp_f32_e32 v38, v38
	v_rcp_f32_e32 v39, v39
	s_nop 0
	v_pk_mul_f32 v[36:37], v[32:33], v[38:39]
	v_pk_mul_f32 v[36:37], v[34:35], v[36:37]
	v_cvt_pk_bf16_f32 v224, v36, v37
; __device__ __forceinline__ float bf2f(unsigned b) { return __uint_as_float(b << 16); }
; __device__ __forceinline__ unsigned pk2(float lo, float hi) { unsigned r; asm("v_cvt_pk_bf16_f32 %0, %1, %2" : "=v"(r) : "v"(lo), "v"(hi)); return r; }
; __device__ __forceinline__ float gelu_t(float x) { return x * __builtin_amdgcn_rcpf(1.f + __expf(-1.5957691216057308f * (x + 0.044715f * x * x * x))); }
; __device__ __forceinline__ void act_item(int item, u16* UP, const u16* HALO, const float* sconv, const float* wconv, const float* bconv, float* out, int lane) {
;     ...
;         for (int t = 0; t < 16; ++t) { const size_t row = (size_t)rb * 64 + tb + t; gw[t] = *(const unsigned*)(UP + row * FF2 + j0); vw[t] = *(const unsigned*)(UP + row * FF2 + FF + j0); }
; #pragma unroll
;         for (int t = 0; t < 16; ++t) {
;             const int row = rb * 64 + tb + t;
;             if (sample && (t & 3) == 0) { const int ns = (row - TP) >> 2; const float* s0 = sconv + (size_t)ns * 2 * FF2;
;                 const f32x2 a = *(const f32x2*)(s0 + j0), b = *(const f32x2*)(s0 + FF + j0), c = *(const f32x2*)(s0 + FF2 + j0), dd = *(const f32x2*)(s0 + FF2 + FF + j0);
;                 g2[0] = a.x; g2[1] = a.y; v2[0] = b.x; v2[1] = b.y; g1[0] = c.x; g1[1] = c.y; v1[0] = dd.x; v1[1] = dd.y; }
;             const float g0[2] = {bf2f(gw[t] & 0xffffu), bf2f(gw[t] >> 16)}, v0[2] = {bf2f(vw[t] & 0xffffu), bf2f(vw[t] >> 16)};
;             float res[2];
; #pragma unroll
;             for (int p = 0; p < 2; ++p) { const float cgv = bg[p] + wgt[0][p] * g2[p] + wgt[1][p] * g1[p] + wgt[2][p] * g0[p];
;                 const float cvv = bv[p] + wvl[0][p] * v2[p] + wvl[1][p] * v1[p] + wvl[2][p] * v0[p]; res[p] = gelu_t(cgv) * cvv;
;                 g2[p] = g1[p]; g1[p] = g0[p]; v2[p] = v1[p]; v1[p] = v0[p]; }
;             *(unsigned*)(UP + (size_t)row * FF2 + j0) = pk2(res[0], res[1]);
	global_store_dword v2, v224, s[66:67]
	s_add_u32 s66, s66, 0x2c00
	s_addc_u32 s67, s67, 0
	global_load_dword v160, v2, s[64:65]
	global_load_dword v161, v3, s[64:65]
	s_add_u32 s64, s64, 0x2c00
	s_addc_u32 s65, s65, 0
	global_load_dword v162, v2, s[64:65]
	global_load_dword v163, v3, s[64:65]
	s_add_u32 s64, s64, 0x2c00
	s_addc_u32 s65, s65, 0
	global_load_dword v164, v2, s[64:65]
	global_load_dword v165, v3, s[64:65]
	s_add_u32 s64, s64, 0x2c00
	s_addc_u32 s65, s65, 0
	global_load_dword v166, v2, s[64:65]
	global_load_dword v167, v3, s[64:65]
	s_add_u32 s64, s64, 0x2c00
	s_addc_u32 s65, s65, 0
	global_load_dword v168, v2, s[64:65]
	global_load_dword v169, v3, s[64:65]
	s_add_u32 s64, s64, 0x2c00
	s_addc_u32 s65, s65, 0
	global_load_dword v170, v2, s[64:65]
	global_load_dword v171, v3, s[64:65]
	s_add_u32 s64, s64, 0x2c00
	s_addc_u32 s65, s65, 0
	global_load_dword v172, v2, s[64:65]
	global_load_dword v173, v3, s[64:65]
	s_add_u32 s64, s64, 0x2c00
	s_addc_u32 s65, s65, 0
	global_load_dword v174, v2, s[64:65]
	global_load_dword v175, v3, s[64:65]
	s_add_u32 s64, s64, 0x2c00
	s_addc_u32 s65, s65, 0
	global_load_dword v176, v2, s[64:65]
	global_load_dword v177, v3, s[64:65]
	s_add_u32 s64, s64, 0x2c00
	s_addc_u32 s65, s65, 0
	global_load_dword v178, v2, s[64:65]
	global_load_dword v179, v3, s[64:65]
	s_add_u32 s64, s64, 0x2c00
	s_addc_u32 s65, s65, 0
	global_load_dword v180, v2, s[64:65]
	global_load_dword v181, v3, s[64:65]
	s_add_u32 s64, s64, 0x2c00
	s_addc_u32 s65, s65, 0
	global_load_dword v182, v2, s[64:65]
	global_load_dword v183, v3, s[64:65]
	s_add_u32 s64, s64, 0x2c00
	s_addc_u32 s65, s65, 0
	global_load_dword v184, v2, s[64:65]
	global_load_dword v185, v3, s[64:65]
	s_add_u32 s64, s64, 0x2c00
	s_addc_u32 s65, s65, 0
	global_load_dword v186, v2, s[64:65]
	global_load_dword v187, v3, s[64:65]
	s_add_u32 s64, s64, 0x2c00
	s_addc_u32 s65, s65, 0
	global_load_dword v188, v2, s[64:65]
	global_load_dword v189, v3, s[64:65]
	s_add_u32 s64, s64, 0x2c00
	s_addc_u32 s65, s65, 0
	global_load_dword v190, v2, s[64:65]
	global_load_dword v191, v3, s[64:65]
	s_add_u32 s64, s64, 0x2c00
	s_addc_u32 s65, s65, 0
	s_waitcnt vmcnt(62)
	v_lshlrev_b32_e32 v24, 16, v192
	v_and_b32_e32 v25, 0xffff0000, v192
	v_lshlrev_b32_e32 v26, 16, v193
	v_and_b32_e32 v27, 0xffff0000, v193
	v_pk_fma_f32 v[32:33], v[4:5], v[28:29], v[16:17]
	v_pk_fma_f32 v[34:35], v[6:7], v[30:31], v[18:19]
	v_pk_fma_f32 v[32:33], v[8:9], v[20:21], v[32:33]
	v_pk_fma_f32 v[34:35], v[10:11], v[22:23], v[34:35]
	v_pk_fma_f32 v[32:33], v[12:13], v[24:25], v[32:33]
	v_pk_fma_f32 v[34:35], v[14:15], v[26:27], v[34:35]
	v_pk_mul_f32 v[36:37], v[32:33], s[58:59]
	v_pk_mul_f32 v[36:37], v[32:33], v[36:37]
	v_pk_fma_f32 v[36:37], v[32:33], v[36:37], v[32:33]
	v_pk_mul_f32 v[36:37], v[36:37], s[60:61]
	v_pk_mul_f32 v[36:37], v[36:37], s[68:69]
	v_exp_f32_e32 v38, v36
	v_exp_f32_e32 v39, v37
	s_nop 0
	v_pk_add_f32 v[38:39], v[38:39], s[82:83]
	v_rcp_f32_e32 v38, v38
	v_rcp_f32_e32 v39, v39
	s_nop 0
	v_pk_mul_f32 v[36:37], v[32:33], v[38:39]
	v_pk_mul_f32 v[36:37], v[34:35], v[36:37]
	v_cvt_pk_bf16_f32 v224, v36, v37
	global_store_dword v2, v224, s[66:67]
	s_add_u32 s66, s66, 0x2c00
	s_addc_u32 s67, s67, 0
	s_waitcnt vmcnt(61)
	v_lshlrev_b32_e32 v28, 16, v194
	v_and_b32_e32 v29, 0xffff0000, v194
	v_lshlrev_b32_e32 v30, 16, v195
	v_and_b32_e32 v31, 0xffff0000, v195
	v_pk_fma_f32 v[32:33], v[4:5], v[20:21], v[16:17]
	v_pk_fma_f32 v[34:35], v[6:7], v[22:23], v[18:19]
	v_pk_fma_f32 v[32:33], v[8:9], v[24:25], v[32:33]
	v_pk_fma_f32 v[34:35], v[10:11], v[26:27], v[34:35]
	v_pk_fma_f32 v[32:33], v[12:13], v[28:29], v[32:33]
	v_pk_fma_f32 v[34:35], v[14:15], v[30:31], v[34:35]
	v_pk_mul_f32 v[36:37], v[32:33], s[58:59]
	v_pk_mul_f32 v[36:37], v[32:33], v[36:37]
	v_pk_fma_f32 v[36:37], v[32:33], v[36:37], v[32:33]
	v_pk_mul_f32 v[36:37], v[36:37], s[60:61]
	v_pk_mul_f32 v[36:37], v[36:37], s[68:69]
	v_exp_f32_e32 v38, v36
	v_exp_f32_e32 v39, v37
	s_nop 0
	v_pk_add_f32 v[38:39], v[38:39], s[82:83]
	v_rcp_f32_e32 v38, v38
	v_rcp_f32_e32 v39, v39
	s_nop 0
	v_pk_mul_f32 v[36:37], v[32:33], v[38:39]
	v_pk_mul_f32 v[36:37], v[34:35], v[36:37]
	v_cvt_pk_bf16_f32 v224, v36, v37
	global_store_dword v2, v224, s[66:67]
	s_add_u32 s66, s66, 0x2c00
	s_addc_u32 s67, s67, 0
	s_waitcnt vmcnt(60)
	v_lshlrev_b32_e32 v20, 16, v196
	v_and_b32_e32 v21, 0xffff0000, v196
	v_lshlrev_b32_e32 v22, 16, v197
	v_and_b32_e32 v23, 0xffff0000, v197
	v_pk_fma_f32 v[32:33], v[4:5], v[24:25], v[16:17]
	v_pk_fma_f32 v[34:35], v[6:7], v[26:27], v[18:19]
	v_pk_fma_f32 v[32:33], v[8:9], v[28:29], v[32:33]
	v_pk_fma_f32 v[34:35], v[10:11], v[30:31], v[34:35]
	v_pk_fma_f32 v[32:33], v[12:13], v[20:21], v[32:33]
	v_pk_fma_f32 v[34:35], v[14:15], v[22:23], v[34:35]
	v_pk_mul_f32 v[36:37], v[32:33], s[58:59]
	v_pk_mul_f32 v[36:37], v[32:33], v[36:37]
	v_pk_fma_f32 v[36:37], v[32:33], v[36:37], v[32:33]
	v_pk_mul_f32 v[36:37], v[36:37], s[60:61]
	v_pk_mul_f32 v[36:37], v[36:37], s[68:69]
	v_exp_f32_e32 v38, v36
	v_exp_f32_e32 v39, v37
	s_nop 0
	v_pk_add_f32 v[38:39], v[38:39], s[82:83]
	v_rcp_f32_e32 v38, v38
	v_rcp_f32_e32 v39, v39
	s_nop 0
	v_pk_mul_f32 v[36:37], v[32:33], v[38:39]
	v_pk_mul_f32 v[36:37], v[34:35], v[36:37]
	v_cvt_pk_bf16_f32 v224, v36, v37
	global_store_dword v2, v224, s[66:67]
	s_add_u32 s66, s66, 0x2c00
	s_addc_u32 s67, s67, 0
	s_waitcnt vmcnt(59)
; __device__ __forceinline__ float bf2f(unsigned b) { return __uint_as_float(b << 16); }
; __device__ __forceinline__ unsigned pk2(float lo, float hi) { unsigned r; asm("v_cvt_pk_bf16_f32 %0, %1, %2" : "=v"(r) : "v"(lo), "v"(hi)); return r; }
; __device__ __forceinline__ float gelu_t(float x) { return x * __builtin_amdgcn_rcpf(1.f + __expf(-1.5957691216057308f * (x + 0.044715f * x * x * x))); }
; __device__ __forceinline__ void act_item(int item, u16* UP, const u16* HALO, const float* sconv, const float* wconv, const float* bconv, float* out, int lane) {
;     ...
;         for (int t = 0; t < 16; ++t) {
;             const int row = rb * 64 + tb + t;
;             if (sample && (t & 3) == 0) { const int ns = (row - TP) >> 2; const float* s0 = sconv + (size_t)ns * 2 * FF2;
;                 const f32x2 a = *(const f32x2*)(s0 + j0), b = *(const f32x2*)(s0 + FF + j0), c = *(const f32x2*)(s0 + FF2 + j0), dd = *(const f32x2*)(s0 + FF2 + FF + j0);
;                 g2[0] = a.x; g2[1] = a.y; v2[0] = b.x; v2[1] = b.y; g1[0] = c.x; g1[1] = c.y; v1[0] = dd.x; v1[1] = dd.y; }
;             const float g0[2] = {bf2f(gw[t] & 0xffffu), bf2f(gw[t] >> 16)}, v0[2] = {bf2f(vw[t] & 0xffffu), bf2f(vw[t] >> 16)};
;             float res[2];
; #pragma unroll
;             for (int p = 0; p < 2; ++p) { const float cgv = bg[p] + wgt[0][p] * g2[p] + wgt[1][p] * g1[p] + wgt[2][p] * g0[p];
;                 const float cvv = bv[p] + wvl[0][p] * v2[p] + wvl[1][p] * v1[p] + wvl[2][p] * v0[p]; res[p] = gelu_t(cgv) * cvv;
;                 g2[p] = g1[p]; g1[p] = g0[p]; v2[p] = v1[p]; v1[p] = v0[p]; }
;             *(unsigned*)(UP + (size_t)row * FF2 + j0) = pk2(res[0], res[1]);
	v_lshlrev_b32_e32 v24, 16, v198
	v_and_b32_e32 v25, 0xffff0000, v198
	v_lshlrev_b32_e32 v26, 16, v199
	v_and_b32_e32 v27, 0xffff0000, v199
	v_pk_fma_f32 v[32:33], v[4:5], v[28:29], v[16:17]
	v_pk_fma_f32 v[34:35], v[6:7], v[30:31], v[18:19]
	v_pk_fma_f32 v[32:33], v[8:9], v[20:21], v[32:33]
	v_pk_fma_f32 v[34:35], v[10:11], v[22:23], v[34:35]
	v_pk_fma_f32 v[32:33], v[12:13], v[24:25], v[32:33]
	v_pk_fma_f32 v[34:35], v[14:15], v[26:27], v[34:35]
	v_pk_mul_f32 v[36:37], v[32:33], s[58:59]
	v_pk_mul_f32 v[36:37], v[32:33], v[36:37]
	v_pk_fma_f32 v[36:37], v[32:33], v[36:37], v[32:33]
	v_pk_mul_f32 v[36:37], v[36:37], s[60:61]
	v_pk_mul_f32 v[36:37], v[36:37], s[68:69]
	v_exp_f32_e32 v38, v36
	v_exp_f32_e32 v39, v37
	s_nop 0
	v_pk_add_f32 v[38:39], v[38:39], s[82:83]
	v_rcp_f32_e32 v38, v38
	v_rcp_f32_e32 v39, v39
	s_nop 0
	v_pk_mul_f32 v[36:37], v[32:33], v[38:39]
	v_pk_mul_f32 v[36:37], v[34:35], v[36:37]
	v_cvt_pk_bf16_f32 v224, v36, v37
	global_store_dword v2, v224, s[66:67]
	s_add_u32 s66, s66, 0x2c00
	s_addc_u32 s67, s67, 0
	s_waitcnt vmcnt(58)
	v_lshlrev_b32_e32 v28, 16, v200
	v_and_b32_e32 v29, 0xffff0000, v200
	v_lshlrev_b32_e32 v30, 16, v201
	v_and_b32_e32 v31, 0xffff0000, v201
	v_pk_fma_f32 v[32:33], v[4:5], v[20:21], v[16:17]
	v_pk_fma_f32 v[34:35], v[6:7], v[22:23], v[18:19]
	v_pk_fma_f32 v[32:33], v[8:9], v[24:25], v[32:33]
	v_pk_fma_f32 v[34:35], v[10:11], v[26:27], v[34:35]
	v_pk_fma_f32 v[32:33], v[12:13], v[28:29], v[32:33]
	v_pk_fma_f32 v[34:35], v[14:15], v[30:31], v[34:35]
	v_pk_mul_f32 v[36:37], v[32:33], s[58:59]
	v_pk_mul_f32 v[36:37], v[32:33], v[36:37]
	v_pk_fma_f32 v[36:37], v[32:33], v[36:37], v[32:33]
	v_pk_mul_f32 v[36:37], v[36:37], s[60:61]
	v_pk_mul_f32 v[36:37], v[36:37], s[68:69]
	v_exp_f32_e32 v38, v36
	v_exp_f32_e32 v39, v37
	s_nop 0
	v_pk_add_f32 v[38:39], v[38:39], s[82:83]
	v_rcp_f32_e32 v38, v38
	v_rcp_f32_e32 v39, v39
	s_nop 0
	v_pk_mul_f32 v[36:37], v[32:33], v[38:39]
	v_pk_mul_f32 v[36:37], v[34:35], v[36:37]
	v_cvt_pk_bf16_f32 v224, v36, v37
	global_store_dword v2, v224, s[66:67]
	s_add_u32 s66, s66, 0x2c00
	s_addc_u32 s67, s67, 0
	s_waitcnt vmcnt(57)
	v_lshlrev_b32_e32 v20, 16, v202
	v_and_b32_e32 v21, 0xffff0000, v202
	v_lshlrev_b32_e32 v22, 16, v203
	v_and_b32_e32 v23, 0xffff0000, v203
	v_pk_fma_f32 v[32:33], v[4:5], v[24:25], v[16:17]
	v_pk_fma_f32 v[34:35], v[6:7], v[26:27], v[18:19]
	v_pk_fma_f32 v[32:33], v[8:9], v[28:29], v[32:33]
	v_pk_fma_f32 v[34:35], v[10:11], v[30:31], v[34:35]
	v_pk_fma_f32 v[32:33], v[12:13], v[20:21], v[32:33]
	v_pk_fma_f32 v[34:35], v[14:15], v[22:23], v[34:35]
	v_pk_mul_f32 v[36:37], v[32:33], s[58:59]
	v_pk_mul_f32 v[36:37], v[32:33], v[36:37]
	v_pk_fma_f32 v[36:37], v[32:33], v[36:37], v[32:33]
	v_pk_mul_f32 v[36:37], v[36:37], s[60:61]
	v_pk_mul_f32 v[36:37], v[36:37], s[68:69]
	v_exp_f32_e32 v38, v36
	v_exp_f32_e32 v39, v37
	s_nop 0
	v_pk_add_f32 v[38:39], v[38:39], s[82:83]
	v_rcp_f32_e32 v38, v38
	v_rcp_f32_e32 v39, v39
	s_nop 0
	v_pk_mul_f32 v[36:37], v[32:33], v[38:39]
	v_pk_mul_f32 v[36:37], v[34:35], v[36:37]
	v_cvt_pk_bf16_f32 v224, v36, v37
	global_store_dword v2, v224, s[66:67]
	s_add_u32 s66, s66, 0x2c00
	s_addc_u32 s67, s67, 0
	s_waitcnt vmcnt(56)
	v_lshlrev_b32_e32 v24, 16, v204
	v_and_b32_e32 v25, 0xffff0000, v204
	v_lshlrev_b32_e32 v26, 16, v205
	v_and_b32_e32 v27, 0xffff0000, v205
	v_pk_fma_f32 v[32:33], v[4:5], v[28:29], v[16:17]
	v_pk_fma_f32 v[34:35], v[6:7], v[30:31], v[18:19]
	v_pk_fma_f32 v[32:33], v[8:9], v[20:21], v[32:33]
	v_pk_fma_f32 v[34:35], v[10:11], v[22:23], v[34:35]
	v_pk_fma_f32 v[32:33], v[12:13], v[24:25], v[32:33]
	v_pk_fma_f32 v[34:35], v[14:15], v[26:27], v[34:35]
	v_pk_mul_f32 v[36:37], v[32:33], s[58:59]
	v_pk_mul_f32 v[36:37], v[32:33], v[36:37]
	v_pk_fma_f32 v[36:37], v[32:33], v[36:37], v[32:33]
	v_pk_mul_f32 v[36:37], v[36:37], s[60:61]
	v_pk_mul_f32 v[36:37], v[36:37], s[68:69]
	v_exp_f32_e32 v38, v36
	v_exp_f32_e32 v39, v37
	s_nop 0
	v_pk_add_f32 v[38:39], v[38:39], s[82:83]
	v_rcp_f32_e32 v38, v38
	v_rcp_f32_e32 v39, v39
	s_nop 0
	v_pk_mul_f32 v[36:37], v[32:33], v[38:39]
	v_pk_mul_f32 v[36:37], v[34:35], v[36:37]
	v_cvt_pk_bf16_f32 v224, v36, v37
	global_store_dword v2, v224, s[66:67]
	s_add_u32 s66, s66, 0x2c00
	s_addc_u32 s67, s67, 0
	s_waitcnt vmcnt(55)
	v_lshlrev_b32_e32 v28, 16, v206
	v_and_b32_e32 v29, 0xffff0000, v206
	v_lshlrev_b32_e32 v30, 16, v207
	v_and_b32_e32 v31, 0xffff0000, v207
	v_pk_fma_f32 v[32:33], v[4:5], v[20:21], v[16:17]
	v_pk_fma_f32 v[34:35], v[6:7], v[22:23], v[18:19]
	v_pk_fma_f32 v[32:33], v[8:9], v[24:25], v[32:33]
	v_pk_fma_f32 v[34:35], v[10:11], v[26:27], v[34:35]
	v_pk_fma_f32 v[32:33], v[12:13], v[28:29], v[32:33]
	v_pk_fma_f32 v[34:35], v[14:15], v[30:31], v[34:35]
	v_pk_mul_f32 v[36:37], v[32:33], s[58:59]
	v_pk_mul_f32 v[36:37], v[32:33], v[36:37]
	v_pk_fma_f32 v[36:37], v[32:33], v[36:37], v[32:33]
	v_pk_mul_f32 v[36:37], v[36:37], s[60:61]
	v_pk_mul_f32 v[36:37], v[36:37], s[68:69]
	v_exp_f32_e32 v38, v36
	v_exp_f32_e32 v39, v37
	s_nop 0
	v_pk_add_f32 v[38:39], v[38:39], s[82:83]
	v_rcp_f32_e32 v38, v38
	v_rcp_f32_e32 v39, v39
	s_nop 0
	v_pk_mul_f32 v[36:37], v[32:33], v[38:39]
	v_pk_mul_f32 v[36:37], v[34:35], v[36:37]
	v_cvt_pk_bf16_f32 v224, v36, v37
	global_store_dword v2, v224, s[66:67]
	s_add_u32 s66, s66, 0x2c00
	s_addc_u32 s67, s67, 0
	s_waitcnt vmcnt(54)
; __device__ __forceinline__ float bf2f(unsigned b) { return __uint_as_float(b << 16); }
; __device__ __forceinline__ unsigned pk2(float lo, float hi) { unsigned r; asm("v_cvt_pk_bf16_f32 %0, %1, %2" : "=v"(r) : "v"(lo), "v"(hi)); return r; }
; __device__ __forceinline__ float gelu_t(float x) { return x * __builtin_amdgcn_rcpf(1.f + __expf(-1.5957691216057308f * (x + 0.044715f * x * x * x))); }
; __device__ __forceinline__ void act_item(int item, u16* UP, const u16* HALO, const float* sconv, const float* wconv, const float* bconv, float* out, int lane) {
;     ...
;         for (int t = 0; t < 16; ++t) {
;             const int row = rb * 64 + tb + t;
;             if (sample && (t & 3) == 0) { const int ns = (row - TP) >> 2; const float* s0 = sconv + (size_t)ns * 2 * FF2;
;                 const f32x2 a = *(const f32x2*)(s0 + j0), b = *(const f32x2*)(s0 + FF + j0), c = *(const f32x2*)(s0 + FF2 + j0), dd = *(const f32x2*)(s0 + FF2 + FF + j0);
;                 g2[0] = a.x; g2[1] = a.y; v2[0] = b.x; v2[1] = b.y; g1[0] = c.x; g1[1] = c.y; v1[0] = dd.x; v1[1] = dd.y; }
;             const float g0[2] = {bf2f(gw[t] & 0xffffu), bf2f(gw[t] >> 16)}, v0[2] = {bf2f(vw[t] & 0xffffu), bf2f(vw[t] >> 16)};
;             float res[2];
; #pragma unroll
;             for (int p = 0; p < 2; ++p) { const float cgv = bg[p] + wgt[0][p] * g2[p] + wgt[1][p] * g1[p] + wgt[2][p] * g0[p];
;                 const float cvv = bv[p] + wvl[0][p] * v2[p] + wvl[1][p] * v1[p] + wvl[2][p] * v0[p]; res[p] = gelu_t(cgv) * cvv;
;                 g2[p] = g1[p]; g1[p] = g0[p]; v2[p] = v1[p]; v1[p] = v0[p]; }
;             *(unsigned*)(UP + (size_t)row * FF2 + j0) = pk2(res[0], res[1]);
	v_lshlrev_b32_e32 v20, 16, v208
	v_and_b32_e32 v21, 0xffff0000, v208
	v_lshlrev_b32_e32 v22, 16, v209
	v_and_b32_e32 v23, 0xffff0000, v209
	v_pk_fma_f32 v[32:33], v[4:5], v[24:25], v[16:17]
	v_pk_fma_f32 v[34:35], v[6:7], v[26:27], v[18:19]
	v_pk_fma_f32 v[32:33], v[8:9], v[28:29], v[32:33]
	v_pk_fma_f32 v[34:35], v[10:11], v[30:31], v[34:35]
	v_pk_fma_f32 v[32:33], v[12:13], v[20:21], v[32:33]
	v_pk_fma_f32 v[34:35], v[14:15], v[22:23], v[34:35]
	v_pk_mul_f32 v[36:37], v[32:33], s[58:59]
	v_pk_mul_f32 v[36:37], v[32:33], v[36:37]
	v_pk_fma_f32 v[36:37], v[32:33], v[36:37], v[32:33]
	v_pk_mul_f32 v[36:37], v[36:37], s[60:61]
	v_pk_mul_f32 v[36:37], v[36:37], s[68:69]
	v_exp_f32_e32 v38, v36
	v_exp_f32_e32 v39, v37
	s_nop 0
	v_pk_add_f32 v[38:39], v[38:39], s[82:83]
	v_rcp_f32_e32 v38, v38
	v_rcp_f32_e32 v39, v39
	s_nop 0
	v_pk_mul_f32 v[36:37], v[32:33], v[38:39]
	v_pk_mul_f32 v[36:37], v[34:35], v[36:37]
	v_cvt_pk_bf16_f32 v224, v36, v37
	global_store_dword v2, v224, s[66:67]
	s_add_u32 s66, s66, 0x2c00
	s_addc_u32 s67, s67, 0
	s_waitcnt vmcnt(53)
	v_lshlrev_b32_e32 v24, 16, v210
	v_and_b32_e32 v25, 0xffff0000, v210
	v_lshlrev_b32_e32 v26, 16, v211
	v_and_b32_e32 v27, 0xffff0000, v211
	v_pk_fma_f32 v[32:33], v[4:5], v[28:29], v[16:17]
	v_pk_fma_f32 v[34:35], v[6:7], v[30:31], v[18:19]
	v_pk_fma_f32 v[32:33], v[8:9], v[20:21], v[32:33]
	v_pk_fma_f32 v[34:35], v[10:11], v[22:23], v[34:35]
	v_pk_fma_f32 v[32:33], v[12:13], v[24:25], v[32:33]
	v_pk_fma_f32 v[34:35], v[14:15], v[26:27], v[34:35]
	v_pk_mul_f32 v[36:37], v[32:33], s[58:59]
	v_pk_mul_f32 v[36:37], v[32:33], v[36:37]
	v_pk_fma_f32 v[36:37], v[32:33], v[36:37], v[32:33]
	v_pk_mul_f32 v[36:37], v[36:37], s[60:61]
	v_pk_mul_f32 v[36:37], v[36:37], s[68:69]
	v_exp_f32_e32 v38, v36
	v_exp_f32_e32 v39, v37
	s_nop 0
	v_pk_add_f32 v[38:39], v[38:39], s[82:83]
	v_rcp_f32_e32 v38, v38
	v_rcp_f32_e32 v39, v39
	s_nop 0
	v_pk_mul_f32 v[36:37], v[32:33], v[38:39]
	v_pk_mul_f32 v[36:37], v[34:35], v[36:37]
	v_cvt_pk_bf16_f32 v224, v36, v37
	global_store_dword v2, v224, s[66:67]
	s_add_u32 s66, s66, 0x2c00
	s_addc_u32 s67, s67, 0
	s_waitcnt vmcnt(52)
	v_lshlrev_b32_e32 v28, 16, v212
	v_and_b32_e32 v29, 0xffff0000, v212
	v_lshlrev_b32_e32 v30, 16, v213
	v_and_b32_e32 v31, 0xffff0000, v213
	v_pk_fma_f32 v[32:33], v[4:5], v[20:21], v[16:17]
	v_pk_fma_f32 v[34:35], v[6:7], v[22:23], v[18:19]
	v_pk_fma_f32 v[32:33], v[8:9], v[24:25], v[32:33]
	v_pk_fma_f32 v[34:35], v[10:11], v[26:27], v[34:35]
	v_pk_fma_f32 v[32:33], v[12:13], v[28:29], v[32:33]
	v_pk_fma_f32 v[34:35], v[14:15], v[30:31], v[34:35]
	v_pk_mul_f32 v[36:37], v[32:33], s[58:59]
	v_pk_mul_f32 v[36:37], v[32:33], v[36:37]
	v_pk_fma_f32 v[36:37], v[32:33], v[36:37], v[32:33]
	v_pk_mul_f32 v[36:37], v[36:37], s[60:61]
	v_pk_mul_f32 v[36:37], v[36:37], s[68:69]
	v_exp_f32_e32 v38, v36
	v_exp_f32_e32 v39, v37
	s_nop 0
	v_pk_add_f32 v[38:39], v[38:39], s[82:83]
	v_rcp_f32_e32 v38, v38
	v_rcp_f32_e32 v39, v39
	s_nop 0
	v_pk_mul_f32 v[36:37], v[32:33], v[38:39]
	v_pk_mul_f32 v[36:37], v[34:35], v[36:37]
	v_cvt_pk_bf16_f32 v224, v36, v37
	global_store_dword v2, v224, s[66:67]
	s_add_u32 s66, s66, 0x2c00
	s_addc_u32 s67, s67, 0
	s_waitcnt vmcnt(51)
	v_lshlrev_b32_e32 v20, 16, v214
	v_and_b32_e32 v21, 0xffff0000, v214
	v_lshlrev_b32_e32 v22, 16, v215
	v_and_b32_e32 v23, 0xffff0000, v215
	v_pk_fma_f32 v[32:33], v[4:5], v[24:25], v[16:17]
	v_pk_fma_f32 v[34:35], v[6:7], v[26:27], v[18:19]
	v_pk_fma_f32 v[32:33], v[8:9], v[28:29], v[32:33]
	v_pk_fma_f32 v[34:35], v[10:11], v[30:31], v[34:35]
	v_pk_fma_f32 v[32:33], v[12:13], v[20:21], v[32:33]
	v_pk_fma_f32 v[34:35], v[14:15], v[22:23], v[34:35]
	v_pk_mul_f32 v[36:37], v[32:33], s[58:59]
	v_pk_mul_f32 v[36:37], v[32:33], v[36:37]
	v_pk_fma_f32 v[36:37], v[32:33], v[36:37], v[32:33]
	v_pk_mul_f32 v[36:37], v[36:37], s[60:61]
	v_pk_mul_f32 v[36:37], v[36:37], s[68:69]
	v_exp_f32_e32 v38, v36
	v_exp_f32_e32 v39, v37
	s_nop 0
	v_pk_add_f32 v[38:39], v[38:39], s[82:83]
	v_rcp_f32_e32 v38, v38
	v_rcp_f32_e32 v39, v39
	s_nop 0
	v_pk_mul_f32 v[36:37], v[32:33], v[38:39]
	v_pk_mul_f32 v[36:37], v[34:35], v[36:37]
	v_cvt_pk_bf16_f32 v224, v36, v37
	global_store_dword v2, v224, s[66:67]
	s_add_u32 s66, s66, 0x2c00
	s_addc_u32 s67, s67, 0
	s_waitcnt vmcnt(50)
	v_lshlrev_b32_e32 v24, 16, v216
	v_and_b32_e32 v25, 0xffff0000, v216
	v_lshlrev_b32_e32 v26, 16, v217
	v_and_b32_e32 v27, 0xffff0000, v217
	v_pk_fma_f32 v[32:33], v[4:5], v[28:29], v[16:17]
	v_pk_fma_f32 v[34:35], v[6:7], v[30:31], v[18:19]
	v_pk_fma_f32 v[32:33], v[8:9], v[20:21], v[32:33]
	v_pk_fma_f32 v[34:35], v[10:11], v[22:23], v[34:35]
	v_pk_fma_f32 v[32:33], v[12:13], v[24:25], v[32:33]
	v_pk_fma_f32 v[34:35], v[14:15], v[26:27], v[34:35]
	v_pk_mul_f32 v[36:37], v[32:33], s[58:59]
	v_pk_mul_f32 v[36:37], v[32:33], v[36:37]
	v_pk_fma_f32 v[36:37], v[32:33], v[36:37], v[32:33]
	v_pk_mul_f32 v[36:37], v[36:37], s[60:61]
	v_pk_mul_f32 v[36:37], v[36:37], s[68:69]
	v_exp_f32_e32 v38, v36
	v_exp_f32_e32 v39, v37
	s_nop 0
	v_pk_add_f32 v[38:39], v[38:39], s[82:83]
	v_rcp_f32_e32 v38, v38
	v_rcp_f32_e32 v39, v39
	s_nop 0
	v_pk_mul_f32 v[36:37], v[32:33], v[38:39]
	v_pk_mul_f32 v[36:37], v[34:35], v[36:37]
	v_cvt_pk_bf16_f32 v224, v36, v37
	global_store_dword v2, v224, s[66:67]
	s_add_u32 s66, s66, 0x2c00
	s_addc_u32 s67, s67, 0
	s_waitcnt vmcnt(49)
; __device__ __forceinline__ float bf2f(unsigned b) { return __uint_as_float(b << 16); }
; __device__ __forceinline__ unsigned pk2(float lo, float hi) { unsigned r; asm("v_cvt_pk_bf16_f32 %0, %1, %2" : "=v"(r) : "v"(lo), "v"(hi)); return r; }
; __device__ __forceinline__ float gelu_t(float x) { return x * __builtin_amdgcn_rcpf(1.f + __expf(-1.5957691216057308f * (x + 0.044715f * x * x * x))); }
; __device__ __forceinline__ void act_item(int item, u16* UP, const u16* HALO, const float* sconv, const float* wconv, const float* bconv, float* out, int lane) {
;     ...
;     for (int tb = 0; tb < 64; tb += 16) {
;         unsigned gw[16], vw[16];
; #pragma unroll
;         for (int t = 0; t < 16; ++t) { const size_t row = (size_t)rb * 64 + tb + t; gw[t] = *(const unsigned*)(UP + row * FF2 + j0); vw[t] = *(const unsigned*)(UP + row * FF2 + FF + j0); }
; #pragma unroll
;         for (int t = 0; t < 16; ++t) {
;             const int row = rb * 64 + tb + t;
;             if (sample && (t & 3) == 0) { const int ns = (row - TP) >> 2; const float* s0 = sconv + (size_t)ns * 2 * FF2;
;                 const f32x2 a = *(const f32x2*)(s0 + j0), b = *(const f32x2*)(s0 + FF + j0), c = *(const f32x2*)(s0 + FF2 + j0), dd = *(const f32x2*)(s0 + FF2 + FF + j0);
;                 g2[0] = a.x; g2[1] = a.y; v2[0] = b.x; v2[1] = b.y; g1[0] = c.x; g1[1] = c.y; v1[0] = dd.x; v1[1] = dd.y; }
;             const float g0[2] = {bf2f(gw[t] & 0xffffu), bf2f(gw[t] >> 16)}, v0[2] = {bf2f(vw[t] & 0xffffu), bf2f(vw[t] >> 16)};
;             float res[2];
; #pragma unroll
;             for (int p = 0; p < 2; ++p) { const float cgv = bg[p] + wgt[0][p] * g2[p] + wgt[1][p] * g1[p] + wgt[2][p] * g0[p];
;                 const float cvv = bv[p] + wvl[0][p] * v2[p] + wvl[1][p] * v1[p] + wvl[2][p] * v0[p]; res[p] = gelu_t(cgv) * cvv;
;                 g2[p] = g1[p]; g1[p] = g0[p]; v2[p] = v1[p]; v1[p] = v0[p]; }
;             *(unsigned*)(UP + (size_t)row * FF2 + j0) = pk2(res[0], res[1]);
	v_lshlrev_b32_e32 v28, 16, v218
	v_and_b32_e32 v29, 0xffff0000, v218
	v_lshlrev_b32_e32 v30, 16, v219
	v_and_b32_e32 v31, 0xffff0000, v219
	v_pk_fma_f32 v[32:33], v[4:5], v[20:21], v[16:17]
	v_pk_fma_f32 v[34:35], v[6:7], v[22:23], v[18:19]
	v_pk_fma_f32 v[32:33], v[8:9], v[24:25], v[32:33]
	v_pk_fma_f32 v[34:35], v[10:11], v[26:27], v[34:35]
	v_pk_fma_f32 v[32:33], v[12:13], v[28:29], v[32:33]
	v_pk_fma_f32 v[34:35], v[14:15], v[30:31], v[34:35]
	v_pk_mul_f32 v[36:37], v[32:33], s[58:59]
	v_pk_mul_f32 v[36:37], v[32:33], v[36:37]
	v_pk_fma_f32 v[36:37], v[32:33], v[36:37], v[32:33]
	v_pk_mul_f32 v[36:37], v[36:37], s[60:61]
	v_pk_mul_f32 v[36:37], v[36:37], s[68:69]
	v_exp_f32_e32 v38, v36
	v_exp_f32_e32 v39, v37
	s_nop 0
	v_pk_add_f32 v[38:39], v[38:39], s[82:83]
	v_rcp_f32_e32 v38, v38
	v_rcp_f32_e32 v39, v39
	s_nop 0
	v_pk_mul_f32 v[36:37], v[32:33], v[38:39]
	v_pk_mul_f32 v[36:37], v[34:35], v[36:37]
	v_cvt_pk_bf16_f32 v224, v36, v37
	global_store_dword v2, v224, s[66:67]
	s_add_u32 s66, s66, 0x2c00
	s_addc_u32 s67, s67, 0
	s_waitcnt vmcnt(48)
	v_lshlrev_b32_e32 v20, 16, v220
	v_and_b32_e32 v21, 0xffff0000, v220
	v_lshlrev_b32_e32 v22, 16, v221
	v_and_b32_e32 v23, 0xffff0000, v221
	v_pk_fma_f32 v[32:33], v[4:5], v[24:25], v[16:17]
	v_pk_fma_f32 v[34:35], v[6:7], v[26:27], v[18:19]
	v_pk_fma_f32 v[32:33], v[8:9], v[28:29], v[32:33]
	v_pk_fma_f32 v[34:35], v[10:11], v[30:31], v[34:35]
	v_pk_fma_f32 v[32:33], v[12:13], v[20:21], v[32:33]
	v_pk_fma_f32 v[34:35], v[14:15], v[22:23], v[34:35]
	v_pk_mul_f32 v[36:37], v[32:33], s[58:59]
	v_pk_mul_f32 v[36:37], v[32:33], v[36:37]
	v_pk_fma_f32 v[36:37], v[32:33], v[36:37], v[32:33]
	v_pk_mul_f32 v[36:37], v[36:37], s[60:61]
	v_pk_mul_f32 v[36:37], v[36:37], s[68:69]
	v_exp_f32_e32 v38, v36
	v_exp_f32_e32 v39, v37
	s_nop 0
	v_pk_add_f32 v[38:39], v[38:39], s[82:83]
	v_rcp_f32_e32 v38, v38
	v_rcp_f32_e32 v39, v39
	s_nop 0
	v_pk_mul_f32 v[36:37], v[32:33], v[38:39]
	v_pk_mul_f32 v[36:37], v[34:35], v[36:37]
	v_cvt_pk_bf16_f32 v224, v36, v37
	global_store_dword v2, v224, s[66:67]
	s_add_u32 s66, s66, 0x2c00
	s_addc_u32 s67, s67, 0
	s_waitcnt vmcnt(47)
	v_lshlrev_b32_e32 v24, 16, v222
	v_and_b32_e32 v25, 0xffff0000, v222
	v_lshlrev_b32_e32 v26, 16, v223
	v_and_b32_e32 v27, 0xffff0000, v223
	v_pk_fma_f32 v[32:33], v[4:5], v[28:29], v[16:17]
	v_pk_fma_f32 v[34:35], v[6:7], v[30:31], v[18:19]
	v_pk_fma_f32 v[32:33], v[8:9], v[20:21], v[32:33]
	v_pk_fma_f32 v[34:35], v[10:11], v[22:23], v[34:35]
	v_pk_fma_f32 v[32:33], v[12:13], v[24:25], v[32:33]
	v_pk_fma_f32 v[34:35], v[14:15], v[26:27], v[34:35]
	v_pk_mul_f32 v[36:37], v[32:33], s[58:59]
	v_pk_mul_f32 v[36:37], v[32:33], v[36:37]
	v_pk_fma_f32 v[36:37], v[32:33], v[36:37], v[32:33]
	v_pk_mul_f32 v[36:37], v[36:37], s[60:61]
	v_pk_mul_f32 v[36:37], v[36:37], s[68:69]
	v_exp_f32_e32 v38, v36
	v_exp_f32_e32 v39, v37
	s_nop 0
	v_pk_add_f32 v[38:39], v[38:39], s[82:83]
	v_rcp_f32_e32 v38, v38
	v_rcp_f32_e32 v39, v39
	s_nop 0
	v_pk_mul_f32 v[36:37], v[32:33], v[38:39]
	v_pk_mul_f32 v[36:37], v[34:35], v[36:37]
	v_cvt_pk_bf16_f32 v224, v36, v37
	global_store_dword v2, v224, s[66:67]
	s_add_u32 s66, s66, 0x2c00
	s_addc_u32 s67, s67, 0
	global_load_dword v192, v2, s[64:65]
	global_load_dword v193, v3, s[64:65]
	s_add_u32 s64, s64, 0x2c00
	s_addc_u32 s65, s65, 0
	global_load_dword v194, v2, s[64:65]
	global_load_dword v195, v3, s[64:65]
	s_add_u32 s64, s64, 0x2c00
	s_addc_u32 s65, s65, 0
	global_load_dword v196, v2, s[64:65]
	global_load_dword v197, v3, s[64:65]
	s_add_u32 s64, s64, 0x2c00
	s_addc_u32 s65, s65, 0
	global_load_dword v198, v2, s[64:65]
	global_load_dword v199, v3, s[64:65]
	s_add_u32 s64, s64, 0x2c00
	s_addc_u32 s65, s65, 0
	global_load_dword v200, v2, s[64:65]
	global_load_dword v201, v3, s[64:65]
	s_add_u32 s64, s64, 0x2c00
	s_addc_u32 s65, s65, 0
	global_load_dword v202, v2, s[64:65]
	global_load_dword v203, v3, s[64:65]
	s_add_u32 s64, s64, 0x2c00
	s_addc_u32 s65, s65, 0
	global_load_dword v204, v2, s[64:65]
	global_load_dword v205, v3, s[64:65]
	s_add_u32 s64, s64, 0x2c00
	s_addc_u32 s65, s65, 0
	global_load_dword v206, v2, s[64:65]
	global_load_dword v207, v3, s[64:65]
	s_add_u32 s64, s64, 0x2c00
	s_addc_u32 s65, s65, 0
	global_load_dword v208, v2, s[64:65]
	global_load_dword v209, v3, s[64:65]
	s_add_u32 s64, s64, 0x2c00
	s_addc_u32 s65, s65, 0
	global_load_dword v210, v2, s[64:65]
	global_load_dword v211, v3, s[64:65]
	s_add_u32 s64, s64, 0x2c00
	s_addc_u32 s65, s65, 0
	global_load_dword v212, v2, s[64:65]
	global_load_dword v213, v3, s[64:65]
	s_add_u32 s64, s64, 0x2c00
	s_addc_u32 s65, s65, 0
	global_load_dword v214, v2, s[64:65]
	global_load_dword v215, v3, s[64:65]
	s_add_u32 s64, s64, 0x2c00
	s_addc_u32 s65, s65, 0
	global_load_dword v216, v2, s[64:65]
	global_load_dword v217, v3, s[64:65]
	s_add_u32 s64, s64, 0x2c00
	s_addc_u32 s65, s65, 0
	global_load_dword v218, v2, s[64:65]
	global_load_dword v219, v3, s[64:65]
	s_add_u32 s64, s64, 0x2c00
	s_addc_u32 s65, s65, 0
	global_load_dword v220, v2, s[64:65]
	global_load_dword v221, v3, s[64:65]
	s_add_u32 s64, s64, 0x2c00
	s_addc_u32 s65, s65, 0
	global_load_dword v222, v2, s[64:65]
	global_load_dword v223, v3, s[64:65]
	s_add_u32 s64, s64, 0x2c00
	s_addc_u32 s65, s65, 0
	s_waitcnt vmcnt(62)
; __device__ __forceinline__ float bf2f(unsigned b) { return __uint_as_float(b << 16); }
; __device__ __forceinline__ unsigned pk2(float lo, float hi) { unsigned r; asm("v_cvt_pk_bf16_f32 %0, %1, %2" : "=v"(r) : "v"(lo), "v"(hi)); return r; }
; __device__ __forceinline__ float gelu_t(float x) { return x * __builtin_amdgcn_rcpf(1.f + __expf(-1.5957691216057308f * (x + 0.044715f * x * x * x))); }
; __device__ __forceinline__ void act_item(int item, u16* UP, const u16* HALO, const float* sconv, const float* wconv, const float* bconv, float* out, int lane) {
;     ...
;         for (int t = 0; t < 16; ++t) {
;             const int row = rb * 64 + tb + t;
;             if (sample && (t & 3) == 0) { const int ns = (row - TP) >> 2; const float* s0 = sconv + (size_t)ns * 2 * FF2;
;                 const f32x2 a = *(const f32x2*)(s0 + j0), b = *(const f32x2*)(s0 + FF + j0), c = *(const f32x2*)(s0 + FF2 + j0), dd = *(const f32x2*)(s0 + FF2 + FF + j0);
;                 g2[0] = a.x; g2[1] = a.y; v2[0] = b.x; v2[1] = b.y; g1[0] = c.x; g1[1] = c.y; v1[0] = dd.x; v1[1] = dd.y; }
;             const float g0[2] = {bf2f(gw[t] & 0xffffu), bf2f(gw[t] >> 16)}, v0[2] = {bf2f(vw[t] & 0xffffu), bf2f(vw[t] >> 16)};
;             float res[2];
; #pragma unroll
;             for (int p = 0; p < 2; ++p) { const float cgv = bg[p] + wgt[0][p] * g2[p] + wgt[1][p] * g1[p] + wgt[2][p] * g0[p];
;                 const float cvv = bv[p] + wvl[0][p] * v2[p] + wvl[1][p] * v1[p] + wvl[2][p] * v0[p]; res[p] = gelu_t(cgv) * cvv;
;                 g2[p] = g1[p]; g1[p] = g0[p]; v2[p] = v1[p]; v1[p] = v0[p]; }
;             *(unsigned*)(UP + (size_t)row * FF2 + j0) = pk2(res[0], res[1]);
	v_lshlrev_b32_e32 v28, 16, v160
	v_and_b32_e32 v29, 0xffff0000, v160
	v_lshlrev_b32_e32 v30, 16, v161
	v_and_b32_e32 v31, 0xffff0000, v161
	v_pk_fma_f32 v[32:33], v[4:5], v[20:21], v[16:17]
	v_pk_fma_f32 v[34:35], v[6:7], v[22:23], v[18:19]
	v_pk_fma_f32 v[32:33], v[8:9], v[24:25], v[32:33]
	v_pk_fma_f32 v[34:35], v[10:11], v[26:27], v[34:35]
	v_pk_fma_f32 v[32:33], v[12:13], v[28:29], v[32:33]
	v_pk_fma_f32 v[34:35], v[14:15], v[30:31], v[34:35]
	v_pk_mul_f32 v[36:37], v[32:33], s[58:59]
	v_pk_mul_f32 v[36:37], v[32:33], v[36:37]
	v_pk_fma_f32 v[36:37], v[32:33], v[36:37], v[32:33]
	v_pk_mul_f32 v[36:37], v[36:37], s[60:61]
	v_pk_mul_f32 v[36:37], v[36:37], s[68:69]
	v_exp_f32_e32 v38, v36
	v_exp_f32_e32 v39, v37
	s_nop 0
	v_pk_add_f32 v[38:39], v[38:39], s[82:83]
	v_rcp_f32_e32 v38, v38
	v_rcp_f32_e32 v39, v39
	s_nop 0
	v_pk_mul_f32 v[36:37], v[32:33], v[38:39]
	v_pk_mul_f32 v[36:37], v[34:35], v[36:37]
	v_cvt_pk_bf16_f32 v224, v36, v37
	global_store_dword v2, v224, s[66:67]
	s_add_u32 s66, s66, 0x2c00
	s_addc_u32 s67, s67, 0
	s_waitcnt vmcnt(61)
	v_lshlrev_b32_e32 v20, 16, v162
	v_and_b32_e32 v21, 0xffff0000, v162
	v_lshlrev_b32_e32 v22, 16, v163
	v_and_b32_e32 v23, 0xffff0000, v163
	v_pk_fma_f32 v[32:33], v[4:5], v[24:25], v[16:17]
	v_pk_fma_f32 v[34:35], v[6:7], v[26:27], v[18:19]
	v_pk_fma_f32 v[32:33], v[8:9], v[28:29], v[32:33]
	v_pk_fma_f32 v[34:35], v[10:11], v[30:31], v[34:35]
	v_pk_fma_f32 v[32:33], v[12:13], v[20:21], v[32:33]
	v_pk_fma_f32 v[34:35], v[14:15], v[22:23], v[34:35]
	v_pk_mul_f32 v[36:37], v[32:33], s[58:59]
	v_pk_mul_f32 v[36:37], v[32:33], v[36:37]
	v_pk_fma_f32 v[36:37], v[32:33], v[36:37], v[32:33]
	v_pk_mul_f32 v[36:37], v[36:37], s[60:61]
	v_pk_mul_f32 v[36:37], v[36:37], s[68:69]
	v_exp_f32_e32 v38, v36
	v_exp_f32_e32 v39, v37
	s_nop 0
	v_pk_add_f32 v[38:39], v[38:39], s[82:83]
	v_rcp_f32_e32 v38, v38
	v_rcp_f32_e32 v39, v39
	s_nop 0
	v_pk_mul_f32 v[36:37], v[32:33], v[38:39]
	v_pk_mul_f32 v[36:37], v[34:35], v[36:37]
	v_cvt_pk_bf16_f32 v224, v36, v37
	global_store_dword v2, v224, s[66:67]
	s_add_u32 s66, s66, 0x2c00
	s_addc_u32 s67, s67, 0
	s_waitcnt vmcnt(60)
	v_lshlrev_b32_e32 v24, 16, v164
	v_and_b32_e32 v25, 0xffff0000, v164
	v_lshlrev_b32_e32 v26, 16, v165
	v_and_b32_e32 v27, 0xffff0000, v165
	v_pk_fma_f32 v[32:33], v[4:5], v[28:29], v[16:17]
	v_pk_fma_f32 v[34:35], v[6:7], v[30:31], v[18:19]
	v_pk_fma_f32 v[32:33], v[8:9], v[20:21], v[32:33]
	v_pk_fma_f32 v[34:35], v[10:11], v[22:23], v[34:35]
	v_pk_fma_f32 v[32:33], v[12:13], v[24:25], v[32:33]
	v_pk_fma_f32 v[34:35], v[14:15], v[26:27], v[34:35]
	v_pk_mul_f32 v[36:37], v[32:33], s[58:59]
	v_pk_mul_f32 v[36:37], v[32:33], v[36:37]
	v_pk_fma_f32 v[36:37], v[32:33], v[36:37], v[32:33]
	v_pk_mul_f32 v[36:37], v[36:37], s[60:61]
	v_pk_mul_f32 v[36:37], v[36:37], s[68:69]
	v_exp_f32_e32 v38, v36
	v_exp_f32_e32 v39, v37
	s_nop 0
	v_pk_add_f32 v[38:39], v[38:39], s[82:83]
	v_rcp_f32_e32 v38, v38
	v_rcp_f32_e32 v39, v39
	s_nop 0
	v_pk_mul_f32 v[36:37], v[32:33], v[38:39]
	v_pk_mul_f32 v[36:37], v[34:35], v[36:37]
	v_cvt_pk_bf16_f32 v224, v36, v37
	global_store_dword v2, v224, s[66:67]
	s_add_u32 s66, s66, 0x2c00
	s_addc_u32 s67, s67, 0
	s_waitcnt vmcnt(59)
	v_lshlrev_b32_e32 v28, 16, v166
	v_and_b32_e32 v29, 0xffff0000, v166
	v_lshlrev_b32_e32 v30, 16, v167
	v_and_b32_e32 v31, 0xffff0000, v167
	v_pk_fma_f32 v[32:33], v[4:5], v[20:21], v[16:17]
	v_pk_fma_f32 v[34:35], v[6:7], v[22:23], v[18:19]
	v_pk_fma_f32 v[32:33], v[8:9], v[24:25], v[32:33]
	v_pk_fma_f32 v[34:35], v[10:11], v[26:27], v[34:35]
	v_pk_fma_f32 v[32:33], v[12:13], v[28:29], v[32:33]
	v_pk_fma_f32 v[34:35], v[14:15], v[30:31], v[34:35]
	v_pk_mul_f32 v[36:37], v[32:33], s[58:59]
	v_pk_mul_f32 v[36:37], v[32:33], v[36:37]
	v_pk_fma_f32 v[36:37], v[32:33], v[36:37], v[32:33]
	v_pk_mul_f32 v[36:37], v[36:37], s[60:61]
	v_pk_mul_f32 v[36:37], v[36:37], s[68:69]
	v_exp_f32_e32 v38, v36
	v_exp_f32_e32 v39, v37
	s_nop 0
	v_pk_add_f32 v[38:39], v[38:39], s[82:83]
	v_rcp_f32_e32 v38, v38
	v_rcp_f32_e32 v39, v39
	s_nop 0
	v_pk_mul_f32 v[36:37], v[32:33], v[38:39]
	v_pk_mul_f32 v[36:37], v[34:35], v[36:37]
	v_cvt_pk_bf16_f32 v224, v36, v37
	global_store_dword v2, v224, s[66:67]
	s_add_u32 s66, s66, 0x2c00
	s_addc_u32 s67, s67, 0
	s_waitcnt vmcnt(58)
	v_lshlrev_b32_e32 v20, 16, v168
	v_and_b32_e32 v21, 0xffff0000, v168
	v_lshlrev_b32_e32 v22, 16, v169
	v_and_b32_e32 v23, 0xffff0000, v169
	v_pk_fma_f32 v[32:33], v[4:5], v[24:25], v[16:17]
	v_pk_fma_f32 v[34:35], v[6:7], v[26:27], v[18:19]
	v_pk_fma_f32 v[32:33], v[8:9], v[28:29], v[32:33]
	v_pk_fma_f32 v[34:35], v[10:11], v[30:31], v[34:35]
	v_pk_fma_f32 v[32:33], v[12:13], v[20:21], v[32:33]
	v_pk_fma_f32 v[34:35], v[14:15], v[22:23], v[34:35]
	v_pk_mul_f32 v[36:37], v[32:33], s[58:59]
	v_pk_mul_f32 v[36:37], v[32:33], v[36:37]
	v_pk_fma_f32 v[36:37], v[32:33], v[36:37], v[32:33]
	v_pk_mul_f32 v[36:37], v[36:37], s[60:61]
	v_pk_mul_f32 v[36:37], v[36:37], s[68:69]
	v_exp_f32_e32 v38, v36
	v_exp_f32_e32 v39, v37
	s_nop 0
	v_pk_add_f32 v[38:39], v[38:39], s[82:83]
	v_rcp_f32_e32 v38, v38
	v_rcp_f32_e32 v39, v39
	s_nop 0
	v_pk_mul_f32 v[36:37], v[32:33], v[38:39]
	v_pk_mul_f32 v[36:37], v[34:35], v[36:37]
	v_cvt_pk_bf16_f32 v224, v36, v37
	global_store_dword v2, v224, s[66:67]
	s_add_u32 s66, s66, 0x2c00
	s_addc_u32 s67, s67, 0
	s_waitcnt vmcnt(57)
; __device__ __forceinline__ float bf2f(unsigned b) { return __uint_as_float(b << 16); }
; __device__ __forceinline__ unsigned pk2(float lo, float hi) { unsigned r; asm("v_cvt_pk_bf16_f32 %0, %1, %2" : "=v"(r) : "v"(lo), "v"(hi)); return r; }
; __device__ __forceinline__ float gelu_t(float x) { return x * __builtin_amdgcn_rcpf(1.f + __expf(-1.5957691216057308f * (x + 0.044715f * x * x * x))); }
; __device__ __forceinline__ void act_item(int item, u16* UP, const u16* HALO, const float* sconv, const float* wconv, const float* bconv, float* out, int lane) {
;     ...
;         for (int t = 0; t < 16; ++t) {
;             const int row = rb * 64 + tb + t;
;             if (sample && (t & 3) == 0) { const int ns = (row - TP) >> 2; const float* s0 = sconv + (size_t)ns * 2 * FF2;
;                 const f32x2 a = *(const f32x2*)(s0 + j0), b = *(const f32x2*)(s0 + FF + j0), c = *(const f32x2*)(s0 + FF2 + j0), dd = *(const f32x2*)(s0 + FF2 + FF + j0);
;                 g2[0] = a.x; g2[1] = a.y; v2[0] = b.x; v2[1] = b.y; g1[0] = c.x; g1[1] = c.y; v1[0] = dd.x; v1[1] = dd.y; }
;             const float g0[2] = {bf2f(gw[t] & 0xffffu), bf2f(gw[t] >> 16)}, v0[2] = {bf2f(vw[t] & 0xffffu), bf2f(vw[t] >> 16)};
;             float res[2];
; #pragma unroll
;             for (int p = 0; p < 2; ++p) { const float cgv = bg[p] + wgt[0][p] * g2[p] + wgt[1][p] * g1[p] + wgt[2][p] * g0[p];
;                 const float cvv = bv[p] + wvl[0][p] * v2[p] + wvl[1][p] * v1[p] + wvl[2][p] * v0[p]; res[p] = gelu_t(cgv) * cvv;
;                 g2[p] = g1[p]; g1[p] = g0[p]; v2[p] = v1[p]; v1[p] = v0[p]; }
;             *(unsigned*)(UP + (size_t)row * FF2 + j0) = pk2(res[0], res[1]);
	v_lshlrev_b32_e32 v24, 16, v170
	v_and_b32_e32 v25, 0xffff0000, v170
	v_lshlrev_b32_e32 v26, 16, v171
	v_and_b32_e32 v27, 0xffff0000, v171
	v_pk_fma_f32 v[32:33], v[4:5], v[28:29], v[16:17]
	v_pk_fma_f32 v[34:35], v[6:7], v[30:31], v[18:19]
	v_pk_fma_f32 v[32:33], v[8:9], v[20:21], v[32:33]
	v_pk_fma_f32 v[34:35], v[10:11], v[22:23], v[34:35]
	v_pk_fma_f32 v[32:33], v[12:13], v[24:25], v[32:33]
	v_pk_fma_f32 v[34:35], v[14:15], v[26:27], v[34:35]
	v_pk_mul_f32 v[36:37], v[32:33], s[58:59]
	v_pk_mul_f32 v[36:37], v[32:33], v[36:37]
	v_pk_fma_f32 v[36:37], v[32:33], v[36:37], v[32:33]
	v_pk_mul_f32 v[36:37], v[36:37], s[60:61]
	v_pk_mul_f32 v[36:37], v[36:37], s[68:69]
	v_exp_f32_e32 v38, v36
	v_exp_f32_e32 v39, v37
	s_nop 0
	v_pk_add_f32 v[38:39], v[38:39], s[82:83]
	v_rcp_f32_e32 v38, v38
	v_rcp_f32_e32 v39, v39
	s_nop 0
	v_pk_mul_f32 v[36:37], v[32:33], v[38:39]
	v_pk_mul_f32 v[36:37], v[34:35], v[36:37]
	v_cvt_pk_bf16_f32 v224, v36, v37
	global_store_dword v2, v224, s[66:67]
	s_add_u32 s66, s66, 0x2c00
	s_addc_u32 s67, s67, 0
	s_waitcnt vmcnt(56)
	v_lshlrev_b32_e32 v28, 16, v172
	v_and_b32_e32 v29, 0xffff0000, v172
	v_lshlrev_b32_e32 v30, 16, v173
	v_and_b32_e32 v31, 0xffff0000, v173
	v_pk_fma_f32 v[32:33], v[4:5], v[20:21], v[16:17]
	v_pk_fma_f32 v[34:35], v[6:7], v[22:23], v[18:19]
	v_pk_fma_f32 v[32:33], v[8:9], v[24:25], v[32:33]
	v_pk_fma_f32 v[34:35], v[10:11], v[26:27], v[34:35]
	v_pk_fma_f32 v[32:33], v[12:13], v[28:29], v[32:33]
	v_pk_fma_f32 v[34:35], v[14:15], v[30:31], v[34:35]
	v_pk_mul_f32 v[36:37], v[32:33], s[58:59]
	v_pk_mul_f32 v[36:37], v[32:33], v[36:37]
	v_pk_fma_f32 v[36:37], v[32:33], v[36:37], v[32:33]
	v_pk_mul_f32 v[36:37], v[36:37], s[60:61]
	v_pk_mul_f32 v[36:37], v[36:37], s[68:69]
	v_exp_f32_e32 v38, v36
	v_exp_f32_e32 v39, v37
	s_nop 0
	v_pk_add_f32 v[38:39], v[38:39], s[82:83]
	v_rcp_f32_e32 v38, v38
	v_rcp_f32_e32 v39, v39
	s_nop 0
	v_pk_mul_f32 v[36:37], v[32:33], v[38:39]
	v_pk_mul_f32 v[36:37], v[34:35], v[36:37]
	v_cvt_pk_bf16_f32 v224, v36, v37
	global_store_dword v2, v224, s[66:67]
	s_add_u32 s66, s66, 0x2c00
	s_addc_u32 s67, s67, 0
	s_waitcnt vmcnt(55)
	v_lshlrev_b32_e32 v20, 16, v174
	v_and_b32_e32 v21, 0xffff0000, v174
	v_lshlrev_b32_e32 v22, 16, v175
	v_and_b32_e32 v23, 0xffff0000, v175
	v_pk_fma_f32 v[32:33], v[4:5], v[24:25], v[16:17]
	v_pk_fma_f32 v[34:35], v[6:7], v[26:27], v[18:19]
	v_pk_fma_f32 v[32:33], v[8:9], v[28:29], v[32:33]
	v_pk_fma_f32 v[34:35], v[10:11], v[30:31], v[34:35]
	v_pk_fma_f32 v[32:33], v[12:13], v[20:21], v[32:33]
	v_pk_fma_f32 v[34:35], v[14:15], v[22:23], v[34:35]
	v_pk_mul_f32 v[36:37], v[32:33], s[58:59]
	v_pk_mul_f32 v[36:37], v[32:33], v[36:37]
	v_pk_fma_f32 v[36:37], v[32:33], v[36:37], v[32:33]
	v_pk_mul_f32 v[36:37], v[36:37], s[60:61]
	v_pk_mul_f32 v[36:37], v[36:37], s[68:69]
	v_exp_f32_e32 v38, v36
	v_exp_f32_e32 v39, v37
	s_nop 0
	v_pk_add_f32 v[38:39], v[38:39], s[82:83]
	v_rcp_f32_e32 v38, v38
	v_rcp_f32_e32 v39, v39
	s_nop 0
	v_pk_mul_f32 v[36:37], v[32:33], v[38:39]
	v_pk_mul_f32 v[36:37], v[34:35], v[36:37]
	v_cvt_pk_bf16_f32 v224, v36, v37
	global_store_dword v2, v224, s[66:67]
	s_add_u32 s66, s66, 0x2c00
	s_addc_u32 s67, s67, 0
	s_waitcnt vmcnt(54)
	v_lshlrev_b32_e32 v24, 16, v176
	v_and_b32_e32 v25, 0xffff0000, v176
	v_lshlrev_b32_e32 v26, 16, v177
	v_and_b32_e32 v27, 0xffff0000, v177
	v_pk_fma_f32 v[32:33], v[4:5], v[28:29], v[16:17]
	v_pk_fma_f32 v[34:35], v[6:7], v[30:31], v[18:19]
	v_pk_fma_f32 v[32:33], v[8:9], v[20:21], v[32:33]
	v_pk_fma_f32 v[34:35], v[10:11], v[22:23], v[34:35]
	v_pk_fma_f32 v[32:33], v[12:13], v[24:25], v[32:33]
	v_pk_fma_f32 v[34:35], v[14:15], v[26:27], v[34:35]
	v_pk_mul_f32 v[36:37], v[32:33], s[58:59]
	v_pk_mul_f32 v[36:37], v[32:33], v[36:37]
	v_pk_fma_f32 v[36:37], v[32:33], v[36:37], v[32:33]
	v_pk_mul_f32 v[36:37], v[36:37], s[60:61]
	v_pk_mul_f32 v[36:37], v[36:37], s[68:69]
	v_exp_f32_e32 v38, v36
	v_exp_f32_e32 v39, v37
	s_nop 0
	v_pk_add_f32 v[38:39], v[38:39], s[82:83]
	v_rcp_f32_e32 v38, v38
	v_rcp_f32_e32 v39, v39
	s_nop 0
	v_pk_mul_f32 v[36:37], v[32:33], v[38:39]
	v_pk_mul_f32 v[36:37], v[34:35], v[36:37]
	v_cvt_pk_bf16_f32 v224, v36, v37
	global_store_dword v2, v224, s[66:67]
	s_add_u32 s66, s66, 0x2c00
	s_addc_u32 s67, s67, 0
	s_waitcnt vmcnt(53)
	v_lshlrev_b32_e32 v28, 16, v178
	v_and_b32_e32 v29, 0xffff0000, v178
	v_lshlrev_b32_e32 v30, 16, v179
	v_and_b32_e32 v31, 0xffff0000, v179
	v_pk_fma_f32 v[32:33], v[4:5], v[20:21], v[16:17]
	v_pk_fma_f32 v[34:35], v[6:7], v[22:23], v[18:19]
	v_pk_fma_f32 v[32:33], v[8:9], v[24:25], v[32:33]
	v_pk_fma_f32 v[34:35], v[10:11], v[26:27], v[34:35]
	v_pk_fma_f32 v[32:33], v[12:13], v[28:29], v[32:33]
	v_pk_fma_f32 v[34:35], v[14:15], v[30:31], v[34:35]
	v_pk_mul_f32 v[36:37], v[32:33], s[58:59]
	v_pk_mul_f32 v[36:37], v[32:33], v[36:37]
	v_pk_fma_f32 v[36:37], v[32:33], v[36:37], v[32:33]
	v_pk_mul_f32 v[36:37], v[36:37], s[60:61]
	v_pk_mul_f32 v[36:37], v[36:37], s[68:69]
	v_exp_f32_e32 v38, v36
	v_exp_f32_e32 v39, v37
	s_nop 0
	v_pk_add_f32 v[38:39], v[38:39], s[82:83]
	v_rcp_f32_e32 v38, v38
	v_rcp_f32_e32 v39, v39
	s_nop 0
	v_pk_mul_f32 v[36:37], v[32:33], v[38:39]
	v_pk_mul_f32 v[36:37], v[34:35], v[36:37]
	v_cvt_pk_bf16_f32 v224, v36, v37
	global_store_dword v2, v224, s[66:67]
	s_add_u32 s66, s66, 0x2c00
	s_addc_u32 s67, s67, 0
	s_waitcnt vmcnt(52)
; __device__ __forceinline__ float bf2f(unsigned b) { return __uint_as_float(b << 16); }
; __device__ __forceinline__ unsigned pk2(float lo, float hi) { unsigned r; asm("v_cvt_pk_bf16_f32 %0, %1, %2" : "=v"(r) : "v"(lo), "v"(hi)); return r; }
; __device__ __forceinline__ float gelu_t(float x) { return x * __builtin_amdgcn_rcpf(1.f + __expf(-1.5957691216057308f * (x + 0.044715f * x * x * x))); }
; __device__ __forceinline__ void act_item(int item, u16* UP, const u16* HALO, const float* sconv, const float* wconv, const float* bconv, float* out, int lane) {
;     ...
;         for (int t = 0; t < 16; ++t) {
;             const int row = rb * 64 + tb + t;
;             if (sample && (t & 3) == 0) { const int ns = (row - TP) >> 2; const float* s0 = sconv + (size_t)ns * 2 * FF2;
;                 const f32x2 a = *(const f32x2*)(s0 + j0), b = *(const f32x2*)(s0 + FF + j0), c = *(const f32x2*)(s0 + FF2 + j0), dd = *(const f32x2*)(s0 + FF2 + FF + j0);
;                 g2[0] = a.x; g2[1] = a.y; v2[0] = b.x; v2[1] = b.y; g1[0] = c.x; g1[1] = c.y; v1[0] = dd.x; v1[1] = dd.y; }
;             const float g0[2] = {bf2f(gw[t] & 0xffffu), bf2f(gw[t] >> 16)}, v0[2] = {bf2f(vw[t] & 0xffffu), bf2f(vw[t] >> 16)};
;             float res[2];
; #pragma unroll
;             for (int p = 0; p < 2; ++p) { const float cgv = bg[p] + wgt[0][p] * g2[p] + wgt[1][p] * g1[p] + wgt[2][p] * g0[p];
;                 const float cvv = bv[p] + wvl[0][p] * v2[p] + wvl[1][p] * v1[p] + wvl[2][p] * v0[p]; res[p] = gelu_t(cgv) * cvv;
;                 g2[p] = g1[p]; g1[p] = g0[p]; v2[p] = v1[p]; v1[p] = v0[p]; }
;             *(unsigned*)(UP + (size_t)row * FF2 + j0) = pk2(res[0], res[1]);
; __global__ void __launch_bounds__(512, 2) fwd_kernel(Args args) {
;     ...
;         for (int it = gw; it < 264 * 22; it += NGW) act_item(it, UP, HALO, args.in[I_SCONV], args.in[I_WCONV], args.in[I_BCONV], out, lane);
	v_lshlrev_b32_e32 v20, 16, v180
	v_and_b32_e32 v21, 0xffff0000, v180
	v_lshlrev_b32_e32 v22, 16, v181
	v_and_b32_e32 v23, 0xffff0000, v181
	v_pk_fma_f32 v[32:33], v[4:5], v[24:25], v[16:17]
	v_pk_fma_f32 v[34:35], v[6:7], v[26:27], v[18:19]
	v_pk_fma_f32 v[32:33], v[8:9], v[28:29], v[32:33]
	v_pk_fma_f32 v[34:35], v[10:11], v[30:31], v[34:35]
	v_pk_fma_f32 v[32:33], v[12:13], v[20:21], v[32:33]
	v_pk_fma_f32 v[34:35], v[14:15], v[22:23], v[34:35]
	v_pk_mul_f32 v[36:37], v[32:33], s[58:59]
	v_pk_mul_f32 v[36:37], v[32:33], v[36:37]
	v_pk_fma_f32 v[36:37], v[32:33], v[36:37], v[32:33]
	v_pk_mul_f32 v[36:37], v[36:37], s[60:61]
	v_pk_mul_f32 v[36:37], v[36:37], s[68:69]
	v_exp_f32_e32 v38, v36
	v_exp_f32_e32 v39, v37
	s_nop 0
	v_pk_add_f32 v[38:39], v[38:39], s[82:83]
	v_rcp_f32_e32 v38, v38
	v_rcp_f32_e32 v39, v39
	s_nop 0
	v_pk_mul_f32 v[36:37], v[32:33], v[38:39]
	v_pk_mul_f32 v[36:37], v[34:35], v[36:37]
	v_cvt_pk_bf16_f32 v224, v36, v37
	global_store_dword v2, v224, s[66:67]
	s_add_u32 s66, s66, 0x2c00
	s_addc_u32 s67, s67, 0
	s_waitcnt vmcnt(51)
	v_lshlrev_b32_e32 v24, 16, v182
	v_and_b32_e32 v25, 0xffff0000, v182
	v_lshlrev_b32_e32 v26, 16, v183
	v_and_b32_e32 v27, 0xffff0000, v183
	v_pk_fma_f32 v[32:33], v[4:5], v[28:29], v[16:17]
	v_pk_fma_f32 v[34:35], v[6:7], v[30:31], v[18:19]
	v_pk_fma_f32 v[32:33], v[8:9], v[20:21], v[32:33]
	v_pk_fma_f32 v[34:35], v[10:11], v[22:23], v[34:35]
	v_pk_fma_f32 v[32:33], v[12:13], v[24:25], v[32:33]
	v_pk_fma_f32 v[34:35], v[14:15], v[26:27], v[34:35]
	v_pk_mul_f32 v[36:37], v[32:33], s[58:59]
	v_pk_mul_f32 v[36:37], v[32:33], v[36:37]
	v_pk_fma_f32 v[36:37], v[32:33], v[36:37], v[32:33]
	v_pk_mul_f32 v[36:37], v[36:37], s[60:61]
	v_pk_mul_f32 v[36:37], v[36:37], s[68:69]
	v_exp_f32_e32 v38, v36
	v_exp_f32_e32 v39, v37
	s_nop 0
	v_pk_add_f32 v[38:39], v[38:39], s[82:83]
	v_rcp_f32_e32 v38, v38
	v_rcp_f32_e32 v39, v39
	s_nop 0
	v_pk_mul_f32 v[36:37], v[32:33], v[38:39]
	v_pk_mul_f32 v[36:37], v[34:35], v[36:37]
	v_cvt_pk_bf16_f32 v224, v36, v37
	global_store_dword v2, v224, s[66:67]
	s_add_u32 s66, s66, 0x2c00
	s_addc_u32 s67, s67, 0
	s_waitcnt vmcnt(50)
	v_lshlrev_b32_e32 v28, 16, v184
	v_and_b32_e32 v29, 0xffff0000, v184
	v_lshlrev_b32_e32 v30, 16, v185
	v_and_b32_e32 v31, 0xffff0000, v185
	v_pk_fma_f32 v[32:33], v[4:5], v[20:21], v[16:17]
	v_pk_fma_f32 v[34:35], v[6:7], v[22:23], v[18:19]
	v_pk_fma_f32 v[32:33], v[8:9], v[24:25], v[32:33]
	v_pk_fma_f32 v[34:35], v[10:11], v[26:27], v[34:35]
	v_pk_fma_f32 v[32:33], v[12:13], v[28:29], v[32:33]
	v_pk_fma_f32 v[34:35], v[14:15], v[30:31], v[34:35]
	v_pk_mul_f32 v[36:37], v[32:33], s[58:59]
	v_pk_mul_f32 v[36:37], v[32:33], v[36:37]
	v_pk_fma_f32 v[36:37], v[32:33], v[36:37], v[32:33]
	v_pk_mul_f32 v[36:37], v[36:37], s[60:61]
	v_pk_mul_f32 v[36:37], v[36:37], s[68:69]
	v_exp_f32_e32 v38, v36
	v_exp_f32_e32 v39, v37
	s_nop 0
	v_pk_add_f32 v[38:39], v[38:39], s[82:83]
	v_rcp_f32_e32 v38, v38
	v_rcp_f32_e32 v39, v39
	s_nop 0
	v_pk_mul_f32 v[36:37], v[32:33], v[38:39]
	v_pk_mul_f32 v[36:37], v[34:35], v[36:37]
	v_cvt_pk_bf16_f32 v224, v36, v37
	global_store_dword v2, v224, s[66:67]
	s_add_u32 s66, s66, 0x2c00
	s_addc_u32 s67, s67, 0
	s_waitcnt vmcnt(49)
	v_lshlrev_b32_e32 v20, 16, v186
	v_and_b32_e32 v21, 0xffff0000, v186
	v_lshlrev_b32_e32 v22, 16, v187
	v_and_b32_e32 v23, 0xffff0000, v187
	v_pk_fma_f32 v[32:33], v[4:5], v[24:25], v[16:17]
	v_pk_fma_f32 v[34:35], v[6:7], v[26:27], v[18:19]
	v_pk_fma_f32 v[32:33], v[8:9], v[28:29], v[32:33]
	v_pk_fma_f32 v[34:35], v[10:11], v[30:31], v[34:35]
	v_pk_fma_f32 v[32:33], v[12:13], v[20:21], v[32:33]
	v_pk_fma_f32 v[34:35], v[14:15], v[22:23], v[34:35]
	v_pk_mul_f32 v[36:37], v[32:33], s[58:59]
	v_pk_mul_f32 v[36:37], v[32:33], v[36:37]
	v_pk_fma_f32 v[36:37], v[32:33], v[36:37], v[32:33]
	v_pk_mul_f32 v[36:37], v[36:37], s[60:61]
	v_pk_mul_f32 v[36:37], v[36:37], s[68:69]
	v_exp_f32_e32 v38, v36
	v_exp_f32_e32 v39, v37
	s_nop 0
	v_pk_add_f32 v[38:39], v[38:39], s[82:83]
	v_rcp_f32_e32 v38, v38
	v_rcp_f32_e32 v39, v39
	s_nop 0
	v_pk_mul_f32 v[36:37], v[32:33], v[38:39]
	v_pk_mul_f32 v[36:37], v[34:35], v[36:37]
	v_cvt_pk_bf16_f32 v224, v36, v37
	global_store_dword v2, v224, s[66:67]
	s_add_u32 s66, s66, 0x2c00
	s_addc_u32 s67, s67, 0
	s_waitcnt vmcnt(48)
	v_lshlrev_b32_e32 v24, 16, v188
	v_and_b32_e32 v25, 0xffff0000, v188
	v_lshlrev_b32_e32 v26, 16, v189
	v_and_b32_e32 v27, 0xffff0000, v189
	v_pk_fma_f32 v[32:33], v[4:5], v[28:29], v[16:17]
	v_pk_fma_f32 v[34:35], v[6:7], v[30:31], v[18:19]
	v_pk_fma_f32 v[32:33], v[8:9], v[20:21], v[32:33]
	v_pk_fma_f32 v[34:35], v[10:11], v[22:23], v[34:35]
	v_pk_fma_f32 v[32:33], v[12:13], v[24:25], v[32:33]
	v_pk_fma_f32 v[34:35], v[14:15], v[26:27], v[34:35]
	v_pk_mul_f32 v[36:37], v[32:33], s[58:59]
	v_pk_mul_f32 v[36:37], v[32:33], v[36:37]
	v_pk_fma_f32 v[36:37], v[32:33], v[36:37], v[32:33]
	v_pk_mul_f32 v[36:37], v[36:37], s[60:61]
	v_pk_mul_f32 v[36:37], v[36:37], s[68:69]
	v_exp_f32_e32 v38, v36
	v_exp_f32_e32 v39, v37
	s_nop 0
	v_pk_add_f32 v[38:39], v[38:39], s[82:83]
	v_rcp_f32_e32 v38, v38
	v_rcp_f32_e32 v39, v39
	s_nop 0
	v_pk_mul_f32 v[36:37], v[32:33], v[38:39]
	v_pk_mul_f32 v[36:37], v[34:35], v[36:37]
	v_cvt_pk_bf16_f32 v224, v36, v37
	global_store_dword v2, v224, s[66:67]
	s_add_u32 s66, s66, 0x2c00
	s_addc_u32 s67, s67, 0
	s_waitcnt vmcnt(47)
	v_lshlrev_b32_e32 v28, 16, v190
	v_and_b32_e32 v29, 0xffff0000, v190
	v_lshlrev_b32_e32 v30, 16, v191
	v_and_b32_e32 v31, 0xffff0000, v191
	v_pk_fma_f32 v[32:33], v[4:5], v[20:21], v[16:17]
	v_pk_fma_f32 v[34:35], v[6:7], v[22:23], v[18:19]
	v_pk_fma_f32 v[32:33], v[8:9], v[24:25], v[32:33]
	v_pk_fma_f32 v[34:35], v[10:11], v[26:27], v[34:35]
	v_pk_fma_f32 v[32:33], v[12:13], v[28:29], v[32:33]
	v_pk_fma_f32 v[34:35], v[14:15], v[30:31], v[34:35]
	v_pk_mul_f32 v[36:37], v[32:33], s[58:59]
	v_pk_mul_f32 v[36:37], v[32:33], v[36:37]
	v_pk_fma_f32 v[36:37], v[32:33], v[36:37], v[32:33]
	v_pk_mul_f32 v[36:37], v[36:37], s[60:61]
	v_pk_mul_f32 v[36:37], v[36:37], s[68:69]
	v_exp_f32_e32 v38, v36
	v_exp_f32_e32 v39, v37
	s_nop 0
	v_pk_add_f32 v[38:39], v[38:39], s[82:83]
	v_rcp_f32_e32 v38, v38
	v_rcp_f32_e32 v39, v39
	s_nop 0
	v_pk_mul_f32 v[36:37], v[32:33], v[38:39]
	v_pk_mul_f32 v[36:37], v[34:35], v[36:37]
	v_cvt_pk_bf16_f32 v224, v36, v37
	global_store_dword v2, v224, s[66:67]
	s_add_u32 s66, s66, 0x2c00
	s_addc_u32 s67, s67, 0
	v_mov_b32_e32 v158, v2
	v_mov_b32_e32 v159, v3
	s_add_u32 s62, s92, 0x4300000
	s_addc_u32 s63, s93, 0
	s_add_i32 s6, s80, s96
	s_cmpk_lt_i32 s6, 0x1000
	s_cbranch_scc1 .Lact_pf_ok
	s_cmpk_gt_i32 s6, 0x17ff
	s_cbranch_scc1 .Lact_pf_issue
	v_readlane_b32 s7, v237, 12
	s_mul_i32 s6, s2, 7
	s_nop 0
	s_cmp_gt_u32 s7, 6
	s_cbranch_scc1 .Lact_pf_issue
	s_add_i32 s6, s6, s7
	s_addk_i32 s6, 0x1000
	s_cmpk_gt_i32 s6, 0x15ff
	s_cbranch_scc1 .Lact_pf_issue
; __device__ __forceinline__ float bf2f(unsigned b) { return __uint_as_float(b << 16); }
; __device__ __forceinline__ unsigned pk2(float lo, float hi) { unsigned r; asm("v_cvt_pk_bf16_f32 %0, %1, %2" : "=v"(r) : "v"(lo), "v"(hi)); return r; }
; __device__ __forceinline__ float gelu_t(float x) { return x * __builtin_amdgcn_rcpf(1.f + __expf(-1.5957691216057308f * (x + 0.044715f * x * x * x))); }
; __device__ __forceinline__ void act_item(int item, u16* UP, const u16* HALO, const float* sconv, const float* wconv, const float* bconv, float* out, int lane) {
;     ...
;         for (int t = 0; t < 16; ++t) { const size_t row = (size_t)rb * 64 + tb + t; gw[t] = *(const unsigned*)(UP + row * FF2 + j0); vw[t] = *(const unsigned*)(UP + row * FF2 + FF + j0); }
; #pragma unroll
;         for (int t = 0; t < 16; ++t) {
;             const int row = rb * 64 + tb + t;
;             if (sample && (t & 3) == 0) { const int ns = (row - TP) >> 2; const float* s0 = sconv + (size_t)ns * 2 * FF2;
;                 const f32x2 a = *(const f32x2*)(s0 + j0), b = *(const f32x2*)(s0 + FF + j0), c = *(const f32x2*)(s0 + FF2 + j0), dd = *(const f32x2*)(s0 + FF2 + FF + j0);
;                 g2[0] = a.x; g2[1] = a.y; v2[0] = b.x; v2[1] = b.y; g1[0] = c.x; g1[1] = c.y; v1[0] = dd.x; v1[1] = dd.y; }
;             const float g0[2] = {bf2f(gw[t] & 0xffffu), bf2f(gw[t] >> 16)}, v0[2] = {bf2f(vw[t] & 0xffffu), bf2f(vw[t] >> 16)};
;             float res[2];
; #pragma unroll
;             for (int p = 0; p < 2; ++p) { const float cgv = bg[p] + wgt[0][p] * g2[p] + wgt[1][p] * g1[p] + wgt[2][p] * g0[p];
;                 const float cvv = bv[p] + wvl[0][p] * v2[p] + wvl[1][p] * v1[p] + wvl[2][p] * v0[p]; res[p] = gelu_t(cgv) * cvv;
;                 g2[p] = g1[p]; g1[p] = g0[p]; v2[p] = v1[p]; v1[p] = v0[p]; }
;             *(unsigned*)(UP + (size_t)row * FF2 + j0) = pk2(res[0], res[1]);
.Lact_pf_ok:
	s_mul_hi_i32 s7, s6, 0x2e8ba2e9
	s_lshr_b32 s62, s7, 31
	s_ashr_i32 s7, s7, 2
	s_add_i32 s7, s7, s62
	s_mul_i32 s62, s7, 22
	s_sub_i32 s62, s6, s62
	v_lshlrev_b32_e32 v158, 2, v128
	v_lshl_add_u32 v158, s62, 8, v158
	v_add_u32_e32 v159, 0x1600, v158
	s_mul_hi_u32 s63, s7, 0xb0000
	s_mul_i32 s62, s7, 0xb0000
	s_add_u32 s62, s92, s62
	s_addc_u32 s63, s93, s63
	s_add_u32 s62, s62, 0x4300000
	s_addc_u32 s63, s63, 0
	s_mov_b32 s97, 1
.Lact_pf_issue:
	global_load_dword v160, v158, s[62:63]
	global_load_dword v161, v159, s[62:63]
	s_add_u32 s62, s62, 0x2c00
	s_addc_u32 s63, s63, 0
	global_load_dword v162, v158, s[62:63]
	global_load_dword v163, v159, s[62:63]
	s_add_u32 s62, s62, 0x2c00
	s_addc_u32 s63, s63, 0
	global_load_dword v164, v158, s[62:63]
	global_load_dword v165, v159, s[62:63]
	s_add_u32 s62, s62, 0x2c00
	s_addc_u32 s63, s63, 0
	global_load_dword v166, v158, s[62:63]
	global_load_dword v167, v159, s[62:63]
	s_add_u32 s62, s62, 0x2c00
	s_addc_u32 s63, s63, 0
	global_load_dword v168, v158, s[62:63]
	global_load_dword v169, v159, s[62:63]
	s_add_u32 s62, s62, 0x2c00
	s_addc_u32 s63, s63, 0
	global_load_dword v170, v158, s[62:63]
	global_load_dword v171, v159, s[62:63]
	s_add_u32 s62, s62, 0x2c00
	s_addc_u32 s63, s63, 0
	global_load_dword v172, v158, s[62:63]
	global_load_dword v173, v159, s[62:63]
	s_add_u32 s62, s62, 0x2c00
	s_addc_u32 s63, s63, 0
	global_load_dword v174, v158, s[62:63]
	global_load_dword v175, v159, s[62:63]
	s_add_u32 s62, s62, 0x2c00
	s_addc_u32 s63, s63, 0
	global_load_dword v176, v158, s[62:63]
	global_load_dword v177, v159, s[62:63]
	s_add_u32 s62, s62, 0x2c00
	s_addc_u32 s63, s63, 0
	global_load_dword v178, v158, s[62:63]
	global_load_dword v179, v159, s[62:63]
	s_add_u32 s62, s62, 0x2c00
	s_addc_u32 s63, s63, 0
	global_load_dword v180, v158, s[62:63]
	global_load_dword v181, v159, s[62:63]
	s_add_u32 s62, s62, 0x2c00
	s_addc_u32 s63, s63, 0
	global_load_dword v182, v158, s[62:63]
	global_load_dword v183, v159, s[62:63]
	s_add_u32 s62, s62, 0x2c00
	s_addc_u32 s63, s63, 0
	global_load_dword v184, v158, s[62:63]
	global_load_dword v185, v159, s[62:63]
	s_add_u32 s62, s62, 0x2c00
	s_addc_u32 s63, s63, 0
	global_load_dword v186, v158, s[62:63]
	global_load_dword v187, v159, s[62:63]
	s_add_u32 s62, s62, 0x2c00
	s_addc_u32 s63, s63, 0
	global_load_dword v188, v158, s[62:63]
	global_load_dword v189, v159, s[62:63]
	s_add_u32 s62, s62, 0x2c00
	s_addc_u32 s63, s63, 0
	global_load_dword v190, v158, s[62:63]
	global_load_dword v191, v159, s[62:63]
	s_add_u32 s62, s62, 0x2c00
	s_addc_u32 s63, s63, 0
	s_waitcnt vmcnt(62)
	v_lshlrev_b32_e32 v20, 16, v192
	v_and_b32_e32 v21, 0xffff0000, v192
	v_lshlrev_b32_e32 v22, 16, v193
	v_and_b32_e32 v23, 0xffff0000, v193
	v_pk_fma_f32 v[32:33], v[4:5], v[24:25], v[16:17]
	v_pk_fma_f32 v[34:35], v[6:7], v[26:27], v[18:19]
	v_pk_fma_f32 v[32:33], v[8:9], v[28:29], v[32:33]
	v_pk_fma_f32 v[34:35], v[10:11], v[30:31], v[34:35]
	v_pk_fma_f32 v[32:33], v[12:13], v[20:21], v[32:33]
	v_pk_fma_f32 v[34:35], v[14:15], v[22:23], v[34:35]
	v_pk_mul_f32 v[36:37], v[32:33], s[58:59]
	v_pk_mul_f32 v[36:37], v[32:33], v[36:37]
	v_pk_fma_f32 v[36:37], v[32:33], v[36:37], v[32:33]
	v_pk_mul_f32 v[36:37], v[36:37], s[60:61]
	v_pk_mul_f32 v[36:37], v[36:37], s[68:69]
	v_exp_f32_e32 v38, v36
	v_exp_f32_e32 v39, v37
	s_nop 0
	v_pk_add_f32 v[38:39], v[38:39], s[82:83]
	v_rcp_f32_e32 v38, v38
	v_rcp_f32_e32 v39, v39
	s_nop 0
	v_pk_mul_f32 v[36:37], v[32:33], v[38:39]
	v_pk_mul_f32 v[36:37], v[34:35], v[36:37]
	v_cvt_pk_bf16_f32 v224, v36, v37
	global_store_dword v2, v224, s[66:67]
	s_add_u32 s66, s66, 0x2c00
	s_addc_u32 s67, s67, 0
	s_waitcnt vmcnt(61)
	v_lshlrev_b32_e32 v24, 16, v194
	v_and_b32_e32 v25, 0xffff0000, v194
	v_lshlrev_b32_e32 v26, 16, v195
	v_and_b32_e32 v27, 0xffff0000, v195
	v_pk_fma_f32 v[32:33], v[4:5], v[28:29], v[16:17]
	v_pk_fma_f32 v[34:35], v[6:7], v[30:31], v[18:19]
	v_pk_fma_f32 v[32:33], v[8:9], v[20:21], v[32:33]
	v_pk_fma_f32 v[34:35], v[10:11], v[22:23], v[34:35]
	v_pk_fma_f32 v[32:33], v[12:13], v[24:25], v[32:33]
	v_pk_fma_f32 v[34:35], v[14:15], v[26:27], v[34:35]
	v_pk_mul_f32 v[36:37], v[32:33], s[58:59]
	v_pk_mul_f32 v[36:37], v[32:33], v[36:37]
	v_pk_fma_f32 v[36:37], v[32:33], v[36:37], v[32:33]
	v_pk_mul_f32 v[36:37], v[36:37], s[60:61]
	v_pk_mul_f32 v[36:37], v[36:37], s[68:69]
	v_exp_f32_e32 v38, v36
	v_exp_f32_e32 v39, v37
	s_nop 0
	v_pk_add_f32 v[38:39], v[38:39], s[82:83]
	v_rcp_f32_e32 v38, v38
	v_rcp_f32_e32 v39, v39
	s_nop 0
	v_pk_mul_f32 v[36:37], v[32:33], v[38:39]
	v_pk_mul_f32 v[36:37], v[34:35], v[36:37]
	v_cvt_pk_bf16_f32 v224, v36, v37
	global_store_dword v2, v224, s[66:67]
	s_add_u32 s66, s66, 0x2c00
	s_addc_u32 s67, s67, 0
	s_waitcnt vmcnt(60)
	v_lshlrev_b32_e32 v28, 16, v196
	v_and_b32_e32 v29, 0xffff0000, v196
	v_lshlrev_b32_e32 v30, 16, v197
	v_and_b32_e32 v31, 0xffff0000, v197
	v_pk_fma_f32 v[32:33], v[4:5], v[20:21], v[16:17]
	v_pk_fma_f32 v[34:35], v[6:7], v[22:23], v[18:19]
	v_pk_fma_f32 v[32:33], v[8:9], v[24:25], v[32:33]
	v_pk_fma_f32 v[34:35], v[10:11], v[26:27], v[34:35]
	v_pk_fma_f32 v[32:33], v[12:13], v[28:29], v[32:33]
	v_pk_fma_f32 v[34:35], v[14:15], v[30:31], v[34:35]
	v_pk_mul_f32 v[36:37], v[32:33], s[58:59]
	v_pk_mul_f32 v[36:37], v[32:33], v[36:37]
	v_pk_fma_f32 v[36:37], v[32:33], v[36:37], v[32:33]
	v_pk_mul_f32 v[36:37], v[36:37], s[60:61]
	v_pk_mul_f32 v[36:37], v[36:37], s[68:69]
	v_exp_f32_e32 v38, v36
	v_exp_f32_e32 v39, v37
	s_nop 0
	v_pk_add_f32 v[38:39], v[38:39], s[82:83]
	v_rcp_f32_e32 v38, v38
	v_rcp_f32_e32 v39, v39
	s_nop 0
	v_pk_mul_f32 v[36:37], v[32:33], v[38:39]
	v_pk_mul_f32 v[36:37], v[34:35], v[36:37]
	v_cvt_pk_bf16_f32 v224, v36, v37
	global_store_dword v2, v224, s[66:67]
	s_add_u32 s66, s66, 0x2c00
	s_addc_u32 s67, s67, 0
	s_waitcnt vmcnt(59)
; __device__ __forceinline__ float bf2f(unsigned b) { return __uint_as_float(b << 16); }
; __device__ __forceinline__ unsigned pk2(float lo, float hi) { unsigned r; asm("v_cvt_pk_bf16_f32 %0, %1, %2" : "=v"(r) : "v"(lo), "v"(hi)); return r; }
; __device__ __forceinline__ float gelu_t(float x) { return x * __builtin_amdgcn_rcpf(1.f + __expf(-1.5957691216057308f * (x + 0.044715f * x * x * x))); }
; __device__ __forceinline__ void act_item(int item, u16* UP, const u16* HALO, const float* sconv, const float* wconv, const float* bconv, float* out, int lane) {
;     ...
;         for (int t = 0; t < 16; ++t) {
;             const int row = rb * 64 + tb + t;
;             if (sample && (t & 3) == 0) { const int ns = (row - TP) >> 2; const float* s0 = sconv + (size_t)ns * 2 * FF2;
;                 const f32x2 a = *(const f32x2*)(s0 + j0), b = *(const f32x2*)(s0 + FF + j0), c = *(const f32x2*)(s0 + FF2 + j0), dd = *(const f32x2*)(s0 + FF2 + FF + j0);
;                 g2[0] = a.x; g2[1] = a.y; v2[0] = b.x; v2[1] = b.y; g1[0] = c.x; g1[1] = c.y; v1[0] = dd.x; v1[1] = dd.y; }
;             const float g0[2] = {bf2f(gw[t] & 0xffffu), bf2f(gw[t] >> 16)}, v0[2] = {bf2f(vw[t] & 0xffffu), bf2f(vw[t] >> 16)};
;             float res[2];
; #pragma unroll
;             for (int p = 0; p < 2; ++p) { const float cgv = bg[p] + wgt[0][p] * g2[p] + wgt[1][p] * g1[p] + wgt[2][p] * g0[p];
;                 const float cvv = bv[p] + wvl[0][p] * v2[p] + wvl[1][p] * v1[p] + wvl[2][p] * v0[p]; res[p] = gelu_t(cgv) * cvv;
;                 g2[p] = g1[p]; g1[p] = g0[p]; v2[p] = v1[p]; v1[p] = v0[p]; }
;             *(unsigned*)(UP + (size_t)row * FF2 + j0) = pk2(res[0], res[1]);
	v_lshlrev_b32_e32 v20, 16, v198
	v_and_b32_e32 v21, 0xffff0000, v198
	v_lshlrev_b32_e32 v22, 16, v199
	v_and_b32_e32 v23, 0xffff0000, v199
	v_pk_fma_f32 v[32:33], v[4:5], v[24:25], v[16:17]
	v_pk_fma_f32 v[34:35], v[6:7], v[26:27], v[18:19]
	v_pk_fma_f32 v[32:33], v[8:9], v[28:29], v[32:33]
	v_pk_fma_f32 v[34:35], v[10:11], v[30:31], v[34:35]
	v_pk_fma_f32 v[32:33], v[12:13], v[20:21], v[32:33]
	v_pk_fma_f32 v[34:35], v[14:15], v[22:23], v[34:35]
	v_pk_mul_f32 v[36:37], v[32:33], s[58:59]
	v_pk_mul_f32 v[36:37], v[32:33], v[36:37]
	v_pk_fma_f32 v[36:37], v[32:33], v[36:37], v[32:33]
	v_pk_mul_f32 v[36:37], v[36:37], s[60:61]
	v_pk_mul_f32 v[36:37], v[36:37], s[68:69]
	v_exp_f32_e32 v38, v36
	v_exp_f32_e32 v39, v37
	s_nop 0
	v_pk_add_f32 v[38:39], v[38:39], s[82:83]
	v_rcp_f32_e32 v38, v38
	v_rcp_f32_e32 v39, v39
	s_nop 0
	v_pk_mul_f32 v[36:37], v[32:33], v[38:39]
	v_pk_mul_f32 v[36:37], v[34:35], v[36:37]
	v_cvt_pk_bf16_f32 v224, v36, v37
	global_store_dword v2, v224, s[66:67]
	s_add_u32 s66, s66, 0x2c00
	s_addc_u32 s67, s67, 0
	s_waitcnt vmcnt(58)
	v_lshlrev_b32_e32 v24, 16, v200
	v_and_b32_e32 v25, 0xffff0000, v200
	v_lshlrev_b32_e32 v26, 16, v201
	v_and_b32_e32 v27, 0xffff0000, v201
	v_pk_fma_f32 v[32:33], v[4:5], v[28:29], v[16:17]
	v_pk_fma_f32 v[34:35], v[6:7], v[30:31], v[18:19]
	v_pk_fma_f32 v[32:33], v[8:9], v[20:21], v[32:33]
	v_pk_fma_f32 v[34:35], v[10:11], v[22:23], v[34:35]
	v_pk_fma_f32 v[32:33], v[12:13], v[24:25], v[32:33]
	v_pk_fma_f32 v[34:35], v[14:15], v[26:27], v[34:35]
	v_pk_mul_f32 v[36:37], v[32:33], s[58:59]
	v_pk_mul_f32 v[36:37], v[32:33], v[36:37]
	v_pk_fma_f32 v[36:37], v[32:33], v[36:37], v[32:33]
	v_pk_mul_f32 v[36:37], v[36:37], s[60:61]
	v_pk_mul_f32 v[36:37], v[36:37], s[68:69]
	v_exp_f32_e32 v38, v36
	v_exp_f32_e32 v39, v37
	s_nop 0
	v_pk_add_f32 v[38:39], v[38:39], s[82:83]
	v_rcp_f32_e32 v38, v38
	v_rcp_f32_e32 v39, v39
	s_nop 0
	v_pk_mul_f32 v[36:37], v[32:33], v[38:39]
	v_pk_mul_f32 v[36:37], v[34:35], v[36:37]
	v_cvt_pk_bf16_f32 v224, v36, v37
	global_store_dword v2, v224, s[66:67]
	s_add_u32 s66, s66, 0x2c00
	s_addc_u32 s67, s67, 0
	s_waitcnt vmcnt(57)
	v_lshlrev_b32_e32 v28, 16, v202
	v_and_b32_e32 v29, 0xffff0000, v202
	v_lshlrev_b32_e32 v30, 16, v203
	v_and_b32_e32 v31, 0xffff0000, v203
	v_pk_fma_f32 v[32:33], v[4:5], v[20:21], v[16:17]
	v_pk_fma_f32 v[34:35], v[6:7], v[22:23], v[18:19]
	v_pk_fma_f32 v[32:33], v[8:9], v[24:25], v[32:33]
	v_pk_fma_f32 v[34:35], v[10:11], v[26:27], v[34:35]
	v_pk_fma_f32 v[32:33], v[12:13], v[28:29], v[32:33]
	v_pk_fma_f32 v[34:35], v[14:15], v[30:31], v[34:35]
	v_pk_mul_f32 v[36:37], v[32:33], s[58:59]
	v_pk_mul_f32 v[36:37], v[32:33], v[36:37]
	v_pk_fma_f32 v[36:37], v[32:33], v[36:37], v[32:33]
	v_pk_mul_f32 v[36:37], v[36:37], s[60:61]
	v_pk_mul_f32 v[36:37], v[36:37], s[68:69]
	v_exp_f32_e32 v38, v36
	v_exp_f32_e32 v39, v37
	s_nop 0
	v_pk_add_f32 v[38:39], v[38:39], s[82:83]
	v_rcp_f32_e32 v38, v38
	v_rcp_f32_e32 v39, v39
	s_nop 0
	v_pk_mul_f32 v[36:37], v[32:33], v[38:39]
	v_pk_mul_f32 v[36:37], v[34:35], v[36:37]
	v_cvt_pk_bf16_f32 v224, v36, v37
	global_store_dword v2, v224, s[66:67]
	s_add_u32 s66, s66, 0x2c00
	s_addc_u32 s67, s67, 0
	s_waitcnt vmcnt(56)
	v_lshlrev_b32_e32 v20, 16, v204
	v_and_b32_e32 v21, 0xffff0000, v204
	v_lshlrev_b32_e32 v22, 16, v205
	v_and_b32_e32 v23, 0xffff0000, v205
	v_pk_fma_f32 v[32:33], v[4:5], v[24:25], v[16:17]
	v_pk_fma_f32 v[34:35], v[6:7], v[26:27], v[18:19]
	v_pk_fma_f32 v[32:33], v[8:9], v[28:29], v[32:33]
	v_pk_fma_f32 v[34:35], v[10:11], v[30:31], v[34:35]
	v_pk_fma_f32 v[32:33], v[12:13], v[20:21], v[32:33]
	v_pk_fma_f32 v[34:35], v[14:15], v[22:23], v[34:35]
	v_pk_mul_f32 v[36:37], v[32:33], s[58:59]
	v_pk_mul_f32 v[36:37], v[32:33], v[36:37]
	v_pk_fma_f32 v[36:37], v[32:33], v[36:37], v[32:33]
	v_pk_mul_f32 v[36:37], v[36:37], s[60:61]
	v_pk_mul_f32 v[36:37], v[36:37], s[68:69]
	v_exp_f32_e32 v38, v36
	v_exp_f32_e32 v39, v37
	s_nop 0
	v_pk_add_f32 v[38:39], v[38:39], s[82:83]
	v_rcp_f32_e32 v38, v38
	v_rcp_f32_e32 v39, v39
	s_nop 0
	v_pk_mul_f32 v[36:37], v[32:33], v[38:39]
	v_pk_mul_f32 v[36:37], v[34:35], v[36:37]
	v_cvt_pk_bf16_f32 v224, v36, v37
	global_store_dword v2, v224, s[66:67]
	s_add_u32 s66, s66, 0x2c00
	s_addc_u32 s67, s67, 0
	s_waitcnt vmcnt(55)
	v_lshlrev_b32_e32 v24, 16, v206
	v_and_b32_e32 v25, 0xffff0000, v206
	v_lshlrev_b32_e32 v26, 16, v207
	v_and_b32_e32 v27, 0xffff0000, v207
	v_pk_fma_f32 v[32:33], v[4:5], v[28:29], v[16:17]
	v_pk_fma_f32 v[34:35], v[6:7], v[30:31], v[18:19]
	v_pk_fma_f32 v[32:33], v[8:9], v[20:21], v[32:33]
	v_pk_fma_f32 v[34:35], v[10:11], v[22:23], v[34:35]
	v_pk_fma_f32 v[32:33], v[12:13], v[24:25], v[32:33]
	v_pk_fma_f32 v[34:35], v[14:15], v[26:27], v[34:35]
	v_pk_mul_f32 v[36:37], v[32:33], s[58:59]
	v_pk_mul_f32 v[36:37], v[32:33], v[36:37]
	v_pk_fma_f32 v[36:37], v[32:33], v[36:37], v[32:33]
	v_pk_mul_f32 v[36:37], v[36:37], s[60:61]
	v_pk_mul_f32 v[36:37], v[36:37], s[68:69]
	v_exp_f32_e32 v38, v36
	v_exp_f32_e32 v39, v37
	s_nop 0
	v_pk_add_f32 v[38:39], v[38:39], s[82:83]
	v_rcp_f32_e32 v38, v38
	v_rcp_f32_e32 v39, v39
	s_nop 0
	v_pk_mul_f32 v[36:37], v[32:33], v[38:39]
	v_pk_mul_f32 v[36:37], v[34:35], v[36:37]
	v_cvt_pk_bf16_f32 v224, v36, v37
	global_store_dword v2, v224, s[66:67]
	s_add_u32 s66, s66, 0x2c00
	s_addc_u32 s67, s67, 0
	s_waitcnt vmcnt(54)
; __device__ __forceinline__ float bf2f(unsigned b) { return __uint_as_float(b << 16); }
; __device__ __forceinline__ unsigned pk2(float lo, float hi) { unsigned r; asm("v_cvt_pk_bf16_f32 %0, %1, %2" : "=v"(r) : "v"(lo), "v"(hi)); return r; }
; __device__ __forceinline__ float gelu_t(float x) { return x * __builtin_amdgcn_rcpf(1.f + __expf(-1.5957691216057308f * (x + 0.044715f * x * x * x))); }
; __device__ __forceinline__ void act_item(int item, u16* UP, const u16* HALO, const float* sconv, const float* wconv, const float* bconv, float* out, int lane) {
;     ...
;         for (int t = 0; t < 16; ++t) {
;             const int row = rb * 64 + tb + t;
;             if (sample && (t & 3) == 0) { const int ns = (row - TP) >> 2; const float* s0 = sconv + (size_t)ns * 2 * FF2;
;                 const f32x2 a = *(const f32x2*)(s0 + j0), b = *(const f32x2*)(s0 + FF + j0), c = *(const f32x2*)(s0 + FF2 + j0), dd = *(const f32x2*)(s0 + FF2 + FF + j0);
;                 g2[0] = a.x; g2[1] = a.y; v2[0] = b.x; v2[1] = b.y; g1[0] = c.x; g1[1] = c.y; v1[0] = dd.x; v1[1] = dd.y; }
;             const float g0[2] = {bf2f(gw[t] & 0xffffu), bf2f(gw[t] >> 16)}, v0[2] = {bf2f(vw[t] & 0xffffu), bf2f(vw[t] >> 16)};
;             float res[2];
; #pragma unroll
;             for (int p = 0; p < 2; ++p) { const float cgv = bg[p] + wgt[0][p] * g2[p] + wgt[1][p] * g1[p] + wgt[2][p] * g0[p];
;                 const float cvv = bv[p] + wvl[0][p] * v2[p] + wvl[1][p] * v1[p] + wvl[2][p] * v0[p]; res[p] = gelu_t(cgv) * cvv;
;                 g2[p] = g1[p]; g1[p] = g0[p]; v2[p] = v1[p]; v1[p] = v0[p]; }
;             *(unsigned*)(UP + (size_t)row * FF2 + j0) = pk2(res[0], res[1]);
	v_lshlrev_b32_e32 v28, 16, v208
	v_and_b32_e32 v29, 0xffff0000, v208
	v_lshlrev_b32_e32 v30, 16, v209
	v_and_b32_e32 v31, 0xffff0000, v209
	v_pk_fma_f32 v[32:33], v[4:5], v[20:21], v[16:17]
	v_pk_fma_f32 v[34:35], v[6:7], v[22:23], v[18:19]
	v_pk_fma_f32 v[32:33], v[8:9], v[24:25], v[32:33]
	v_pk_fma_f32 v[34:35], v[10:11], v[26:27], v[34:35]
	v_pk_fma_f32 v[32:33], v[12:13], v[28:29], v[32:33]
	v_pk_fma_f32 v[34:35], v[14:15], v[30:31], v[34:35]
	v_pk_mul_f32 v[36:37], v[32:33], s[58:59]
	v_pk_mul_f32 v[36:37], v[32:33], v[36:37]
	v_pk_fma_f32 v[36:37], v[32:33], v[36:37], v[32:33]
	v_pk_mul_f32 v[36:37], v[36:37], s[60:61]
	v_pk_mul_f32 v[36:37], v[36:37], s[68:69]
	v_exp_f32_e32 v38, v36
	v_exp_f32_e32 v39, v37
	s_nop 0
	v_pk_add_f32 v[38:39], v[38:39], s[82:83]
	v_rcp_f32_e32 v38, v38
	v_rcp_f32_e32 v39, v39
	s_nop 0
	v_pk_mul_f32 v[36:37], v[32:33], v[38:39]
	v_pk_mul_f32 v[36:37], v[34:35], v[36:37]
	v_cvt_pk_bf16_f32 v224, v36, v37
	global_store_dword v2, v224, s[66:67]
	s_add_u32 s66, s66, 0x2c00
	s_addc_u32 s67, s67, 0
	s_waitcnt vmcnt(53)
	v_lshlrev_b32_e32 v20, 16, v210
	v_and_b32_e32 v21, 0xffff0000, v210
	v_lshlrev_b32_e32 v22, 16, v211
	v_and_b32_e32 v23, 0xffff0000, v211
	v_pk_fma_f32 v[32:33], v[4:5], v[24:25], v[16:17]
	v_pk_fma_f32 v[34:35], v[6:7], v[26:27], v[18:19]
	v_pk_fma_f32 v[32:33], v[8:9], v[28:29], v[32:33]
	v_pk_fma_f32 v[34:35], v[10:11], v[30:31], v[34:35]
	v_pk_fma_f32 v[32:33], v[12:13], v[20:21], v[32:33]
	v_pk_fma_f32 v[34:35], v[14:15], v[22:23], v[34:35]
	v_pk_mul_f32 v[36:37], v[32:33], s[58:59]
	v_pk_mul_f32 v[36:37], v[32:33], v[36:37]
	v_pk_fma_f32 v[36:37], v[32:33], v[36:37], v[32:33]
	v_pk_mul_f32 v[36:37], v[36:37], s[60:61]
	v_pk_mul_f32 v[36:37], v[36:37], s[68:69]
	v_exp_f32_e32 v38, v36
	v_exp_f32_e32 v39, v37
	s_nop 0
	v_pk_add_f32 v[38:39], v[38:39], s[82:83]
	v_rcp_f32_e32 v38, v38
	v_rcp_f32_e32 v39, v39
	s_nop 0
	v_pk_mul_f32 v[36:37], v[32:33], v[38:39]
	v_pk_mul_f32 v[36:37], v[34:35], v[36:37]
	v_cvt_pk_bf16_f32 v224, v36, v37
	global_store_dword v2, v224, s[66:67]
	s_add_u32 s66, s66, 0x2c00
	s_addc_u32 s67, s67, 0
	s_waitcnt vmcnt(52)
	v_lshlrev_b32_e32 v24, 16, v212
	v_and_b32_e32 v25, 0xffff0000, v212
	v_lshlrev_b32_e32 v26, 16, v213
	v_and_b32_e32 v27, 0xffff0000, v213
	v_pk_fma_f32 v[32:33], v[4:5], v[28:29], v[16:17]
	v_pk_fma_f32 v[34:35], v[6:7], v[30:31], v[18:19]
	v_pk_fma_f32 v[32:33], v[8:9], v[20:21], v[32:33]
	v_pk_fma_f32 v[34:35], v[10:11], v[22:23], v[34:35]
	v_pk_fma_f32 v[32:33], v[12:13], v[24:25], v[32:33]
	v_pk_fma_f32 v[34:35], v[14:15], v[26:27], v[34:35]
	v_pk_mul_f32 v[36:37], v[32:33], s[58:59]
	v_pk_mul_f32 v[36:37], v[32:33], v[36:37]
	v_pk_fma_f32 v[36:37], v[32:33], v[36:37], v[32:33]
	v_pk_mul_f32 v[36:37], v[36:37], s[60:61]
	v_pk_mul_f32 v[36:37], v[36:37], s[68:69]
	v_exp_f32_e32 v38, v36
	v_exp_f32_e32 v39, v37
	s_nop 0
	v_pk_add_f32 v[38:39], v[38:39], s[82:83]
	v_rcp_f32_e32 v38, v38
	v_rcp_f32_e32 v39, v39
	s_nop 0
	v_pk_mul_f32 v[36:37], v[32:33], v[38:39]
	v_pk_mul_f32 v[36:37], v[34:35], v[36:37]
	v_cvt_pk_bf16_f32 v224, v36, v37
	global_store_dword v2, v224, s[66:67]
	s_add_u32 s66, s66, 0x2c00
	s_addc_u32 s67, s67, 0
	s_waitcnt vmcnt(51)
	v_lshlrev_b32_e32 v28, 16, v214
	v_and_b32_e32 v29, 0xffff0000, v214
	v_lshlrev_b32_e32 v30, 16, v215
	v_and_b32_e32 v31, 0xffff0000, v215
	v_pk_fma_f32 v[32:33], v[4:5], v[20:21], v[16:17]
	v_pk_fma_f32 v[34:35], v[6:7], v[22:23], v[18:19]
	v_pk_fma_f32 v[32:33], v[8:9], v[24:25], v[32:33]
	v_pk_fma_f32 v[34:35], v[10:11], v[26:27], v[34:35]
	v_pk_fma_f32 v[32:33], v[12:13], v[28:29], v[32:33]
	v_pk_fma_f32 v[34:35], v[14:15], v[30:31], v[34:35]
	v_pk_mul_f32 v[36:37], v[32:33], s[58:59]
	v_pk_mul_f32 v[36:37], v[32:33], v[36:37]
	v_pk_fma_f32 v[36:37], v[32:33], v[36:37], v[32:33]
	v_pk_mul_f32 v[36:37], v[36:37], s[60:61]
	v_pk_mul_f32 v[36:37], v[36:37], s[68:69]
	v_exp_f32_e32 v38, v36
	v_exp_f32_e32 v39, v37
	s_nop 0
	v_pk_add_f32 v[38:39], v[38:39], s[82:83]
	v_rcp_f32_e32 v38, v38
	v_rcp_f32_e32 v39, v39
	s_nop 0
	v_pk_mul_f32 v[36:37], v[32:33], v[38:39]
	v_pk_mul_f32 v[36:37], v[34:35], v[36:37]
	v_cvt_pk_bf16_f32 v224, v36, v37
	global_store_dword v2, v224, s[66:67]
	s_add_u32 s66, s66, 0x2c00
	s_addc_u32 s67, s67, 0
	s_waitcnt vmcnt(50)
; __device__ __forceinline__ float bf2f(unsigned b) { return __uint_as_float(b << 16); }
; __device__ __forceinline__ unsigned pk2(float lo, float hi) { unsigned r; asm("v_cvt_pk_bf16_f32 %0, %1, %2" : "=v"(r) : "v"(lo), "v"(hi)); return r; }
; __device__ __forceinline__ float gelu_t(float x) { return x * __builtin_amdgcn_rcpf(1.f + __expf(-1.5957691216057308f * (x + 0.044715f * x * x * x))); }
; __device__ __forceinline__ void act_item(int item, u16* UP, const u16* HALO, const float* sconv, const float* wconv, const float* bconv, float* out, int lane) {
;     ...
;         for (int t = 0; t < 16; ++t) {
;             const int row = rb * 64 + tb + t;
;             if (sample && (t & 3) == 0) { const int ns = (row - TP) >> 2; const float* s0 = sconv + (size_t)ns * 2 * FF2;
;                 const f32x2 a = *(const f32x2*)(s0 + j0), b = *(const f32x2*)(s0 + FF + j0), c = *(const f32x2*)(s0 + FF2 + j0), dd = *(const f32x2*)(s0 + FF2 + FF + j0);
;                 g2[0] = a.x; g2[1] = a.y; v2[0] = b.x; v2[1] = b.y; g1[0] = c.x; g1[1] = c.y; v1[0] = dd.x; v1[1] = dd.y; }
;             const float g0[2] = {bf2f(gw[t] & 0xffffu), bf2f(gw[t] >> 16)}, v0[2] = {bf2f(vw[t] & 0xffffu), bf2f(vw[t] >> 16)};
;             float res[2];
; #pragma unroll
;             for (int p = 0; p < 2; ++p) { const float cgv = bg[p] + wgt[0][p] * g2[p] + wgt[1][p] * g1[p] + wgt[2][p] * g0[p];
;                 const float cvv = bv[p] + wvl[0][p] * v2[p] + wvl[1][p] * v1[p] + wvl[2][p] * v0[p]; res[p] = gelu_t(cgv) * cvv;
;                 g2[p] = g1[p]; g1[p] = g0[p]; v2[p] = v1[p]; v1[p] = v0[p]; }
;             *(unsigned*)(UP + (size_t)row * FF2 + j0) = pk2(res[0], res[1]);
;             if (!sample) { const int tq = row & 2047; if (tq >= 2046) { float* o = out + O_CONVP + ((size_t)(row >> 11) * 2 + (tq - 2046)) * FF2;
;                     *(f32x2*)(o + j0) = (f32x2){g0[0], g0[1]}; *(f32x2*)(o + FF + j0) = (f32x2){v0[0], v0[1]}; } }
	v_lshlrev_b32_e32 v20, 16, v216
	v_and_b32_e32 v21, 0xffff0000, v216
	v_lshlrev_b32_e32 v22, 16, v217
	v_and_b32_e32 v23, 0xffff0000, v217
	v_pk_fma_f32 v[32:33], v[4:5], v[24:25], v[16:17]
	v_pk_fma_f32 v[34:35], v[6:7], v[26:27], v[18:19]
	v_pk_fma_f32 v[32:33], v[8:9], v[28:29], v[32:33]
	v_pk_fma_f32 v[34:35], v[10:11], v[30:31], v[34:35]
	v_pk_fma_f32 v[32:33], v[12:13], v[20:21], v[32:33]
	v_pk_fma_f32 v[34:35], v[14:15], v[22:23], v[34:35]
	v_pk_mul_f32 v[36:37], v[32:33], s[58:59]
	v_pk_mul_f32 v[36:37], v[32:33], v[36:37]
	v_pk_fma_f32 v[36:37], v[32:33], v[36:37], v[32:33]
	v_pk_mul_f32 v[36:37], v[36:37], s[60:61]
	v_pk_mul_f32 v[36:37], v[36:37], s[68:69]
	v_exp_f32_e32 v38, v36
	v_exp_f32_e32 v39, v37
	s_nop 0
	v_pk_add_f32 v[38:39], v[38:39], s[82:83]
	v_rcp_f32_e32 v38, v38
	v_rcp_f32_e32 v39, v39
	s_nop 0
	v_pk_mul_f32 v[36:37], v[32:33], v[38:39]
	v_pk_mul_f32 v[36:37], v[34:35], v[36:37]
	v_cvt_pk_bf16_f32 v224, v36, v37
	global_store_dword v2, v224, s[66:67]
	s_add_u32 s66, s66, 0x2c00
	s_addc_u32 s67, s67, 0
	s_waitcnt vmcnt(49)
	v_lshlrev_b32_e32 v24, 16, v218
	v_and_b32_e32 v25, 0xffff0000, v218
	v_lshlrev_b32_e32 v26, 16, v219
	v_and_b32_e32 v27, 0xffff0000, v219
	v_pk_fma_f32 v[32:33], v[4:5], v[28:29], v[16:17]
	v_pk_fma_f32 v[34:35], v[6:7], v[30:31], v[18:19]
	v_pk_fma_f32 v[32:33], v[8:9], v[20:21], v[32:33]
	v_pk_fma_f32 v[34:35], v[10:11], v[22:23], v[34:35]
	v_pk_fma_f32 v[32:33], v[12:13], v[24:25], v[32:33]
	v_pk_fma_f32 v[34:35], v[14:15], v[26:27], v[34:35]
	v_pk_mul_f32 v[36:37], v[32:33], s[58:59]
	v_pk_mul_f32 v[36:37], v[32:33], v[36:37]
	v_pk_fma_f32 v[36:37], v[32:33], v[36:37], v[32:33]
	v_pk_mul_f32 v[36:37], v[36:37], s[60:61]
	v_pk_mul_f32 v[36:37], v[36:37], s[68:69]
	v_exp_f32_e32 v38, v36
	v_exp_f32_e32 v39, v37
	s_nop 0
	v_pk_add_f32 v[38:39], v[38:39], s[82:83]
	v_rcp_f32_e32 v38, v38
	v_rcp_f32_e32 v39, v39
	s_nop 0
	v_pk_mul_f32 v[36:37], v[32:33], v[38:39]
	v_pk_mul_f32 v[36:37], v[34:35], v[36:37]
	v_cvt_pk_bf16_f32 v224, v36, v37
	global_store_dword v2, v224, s[66:67]
	s_add_u32 s66, s66, 0x2c00
	s_addc_u32 s67, s67, 0
	s_waitcnt vmcnt(48)
	v_lshlrev_b32_e32 v28, 16, v220
	v_and_b32_e32 v29, 0xffff0000, v220
	v_lshlrev_b32_e32 v30, 16, v221
	v_and_b32_e32 v31, 0xffff0000, v221
	v_pk_fma_f32 v[32:33], v[4:5], v[20:21], v[16:17]
	v_pk_fma_f32 v[34:35], v[6:7], v[22:23], v[18:19]
	v_pk_fma_f32 v[32:33], v[8:9], v[24:25], v[32:33]
	v_pk_fma_f32 v[34:35], v[10:11], v[26:27], v[34:35]
	v_pk_fma_f32 v[32:33], v[12:13], v[28:29], v[32:33]
	v_pk_fma_f32 v[34:35], v[14:15], v[30:31], v[34:35]
	v_pk_mul_f32 v[36:37], v[32:33], s[58:59]
	v_pk_mul_f32 v[36:37], v[32:33], v[36:37]
	v_pk_fma_f32 v[36:37], v[32:33], v[36:37], v[32:33]
	v_pk_mul_f32 v[36:37], v[36:37], s[60:61]
	v_pk_mul_f32 v[36:37], v[36:37], s[68:69]
	v_exp_f32_e32 v38, v36
	v_exp_f32_e32 v39, v37
	s_cmp_lg_u32 s1, 31
	s_cbranch_scc1 .Lact_ncs0
	s_lshr_b32 s6, s0, 5
	s_lshl_b32 s6, s6, 1
	s_mul_i32 s6, s6, 0x5800
	s_add_u32 s6, s3, s6
	s_addc_u32 s7, s21, 0
	global_store_dwordx2 v1, v[28:29], s[6:7]
	s_add_u32 s6, s6, 0x2c00
	s_addc_u32 s7, s7, 0
	global_store_dwordx2 v1, v[30:31], s[6:7]
.Lact_ncs0:
	v_pk_add_f32 v[38:39], v[38:39], s[82:83]
	v_rcp_f32_e32 v38, v38
	v_rcp_f32_e32 v39, v39
	s_nop 0
	v_pk_mul_f32 v[36:37], v[32:33], v[38:39]
	v_pk_mul_f32 v[36:37], v[34:35], v[36:37]
	v_cvt_pk_bf16_f32 v224, v36, v37
	global_store_dword v2, v224, s[66:67]
	s_add_u32 s66, s66, 0x2c00
	s_addc_u32 s67, s67, 0
	s_waitcnt vmcnt(47)
	v_lshlrev_b32_e32 v20, 16, v222
	v_and_b32_e32 v21, 0xffff0000, v222
	v_lshlrev_b32_e32 v22, 16, v223
	v_and_b32_e32 v23, 0xffff0000, v223
	v_pk_fma_f32 v[32:33], v[4:5], v[24:25], v[16:17]
	v_pk_fma_f32 v[34:35], v[6:7], v[26:27], v[18:19]
	v_pk_fma_f32 v[32:33], v[8:9], v[28:29], v[32:33]
	v_pk_fma_f32 v[34:35], v[10:11], v[30:31], v[34:35]
	v_pk_fma_f32 v[32:33], v[12:13], v[20:21], v[32:33]
	v_pk_fma_f32 v[34:35], v[14:15], v[22:23], v[34:35]
	v_pk_mul_f32 v[36:37], v[32:33], s[58:59]
	v_pk_mul_f32 v[36:37], v[32:33], v[36:37]
	v_pk_fma_f32 v[36:37], v[32:33], v[36:37], v[32:33]
	v_pk_mul_f32 v[36:37], v[36:37], s[60:61]
	v_pk_mul_f32 v[36:37], v[36:37], s[68:69]
	v_exp_f32_e32 v38, v36
	v_exp_f32_e32 v39, v37
	s_cmp_lg_u32 s1, 31
	s_cbranch_scc1 .Lact_ncs1
	s_lshr_b32 s6, s0, 5
	s_lshl_b32 s6, s6, 1
	s_add_i32 s6, s6, 1
	s_mul_i32 s6, s6, 0x5800
	s_add_u32 s6, s3, s6
	s_addc_u32 s7, s21, 0
	global_store_dwordx2 v1, v[20:21], s[6:7]
	s_add_u32 s6, s6, 0x2c00
	s_addc_u32 s7, s7, 0
	global_store_dwordx2 v1, v[22:23], s[6:7]
